# resid GEMM epilogues (P5,P8): issue both cache-line x loads of each 16-row block together (epilogue load de-serialisation)
# speedup vs baseline: 1.0031x; 1.0031x over previous
; __device__ __forceinline__ void resid_tile256(const Params& p, int l, const bf16_t* A, int lda, int nk, const bf16_t* Wt, int ldb, int goff, bool x_from_input,
;                                               const float* lng, const float* lnb, int row0, int nt256, unsigned char* lds, int tid) {
;     ...
; #pragma unroll
;     for (int m = 0; m < 8; ++m) {
;         const int lr = wr * 128 + m * 16 + fr, pp = pp0 + lr;
;         const float* xi = x_rd(p, x_from_input, b, pp);
;         float* xo = x_wr(p, b, pp);
;         float mean = 0.f, rstd = 1.f;
;         if (!x_from_input) { const size_t row = (size_t)row0 + lr; mean = stats[row * 2]; rstd = stats[row * 2 + 1]; }
; #pragma unroll
;         for (int n = 0; n < 4; ++n) {
;             const int col = nt256 * 256 + wc * 64 + n * 16 + fq * 4;
;             f32x4 xv = *(const f32x4*)(xi + col); const f32x4 g4 = *(const f32x4*)(gv + col);
;             if (!x_from_input) {
;                 const f32x4 lg = *(const f32x4*)(lng + col), lb = *(const f32x4*)(lnb + col);
; #pragma unroll
;                 for (int j = 0; j < 4; ++j) xv[j] = (xv[j] - mean) * rstd * lg[j] + lb[j];
;             }
;             f32x4 o;
; #pragma unroll
;             for (int j = 0; j < 4; ++j) o[j] = ALPHA * xv[j] + g4[j] * acc[m][n][j];
;             *(f32x4*)(xo + col) = o;
;         }
.LBB0_809:
	s_mul_hi_i32 s5, s84, 0x38e38e39
	s_lshr_b32 s6, s5, 31
	s_ashr_i32 s5, s5, 9
	s_add_i32 s5, s5, s6
	s_mulk_i32 s5, 0x900
	s_sub_i32 s78, s84, s5
	s_cmpk_gt_i32 s78, 0xff
	s_cselect_b32 s5, s4, 16
	s_ashr_i32 s6, s5, 31
	s_add_u32 s5, s69, s5
	s_addc_u32 s6, s68, s6
	s_mulk_i32 s6, 0x6000
	s_mul_hi_u32 s7, s5, 0x6000
	s_add_i32 s7, s7, s6
	s_mulk_i32 s5, 0x6000
	v_readlane_b32 s6, v255, 50
	s_add_u32 vcc_lo, s6, s5
	s_addc_u32 vcc_hi, s39, s7
	s_ashr_i32 s5, s4, 31
	v_lshl_or_b32 v158, s76, 8, v178
	s_lshl_b64 s[76:77], s[4:5], 23
	s_lshl_b64 s[6:7], s[4:5], 20
	s_add_u32 s79, s57, s76
	s_addc_u32 s81, s56, s77
	v_add_u32_e32 v128, s78, v136
	s_add_u32 s80, s90, s6
	v_add_u32_e32 v130, 0xffffff00, v128
	s_addc_u32 s86, s75, s7
	v_cmp_gt_i32_e64 s[4:5], s88, v128
	v_ashrrev_i32_e32 v129, 31, v128
	v_mov_b32_e32 v131, s86
	v_cndmask_b32_e64 v128, v130, v128, s[4:5]
	v_mov_b32_e32 v130, s81
	v_cndmask_b32_e64 v129, 0, v129, s[4:5]
	v_cndmask_b32_e64 v131, v130, v131, s[4:5]
	v_mov_b32_e32 v130, s79
	v_mov_b32_e32 v132, s80
	v_cndmask_b32_e64 v130, v130, v132, s[4:5]
	v_lshlrev_b64 v[166:167], 12, v[128:129]
	v_ashrrev_i32_e32 v159, 31, v158
	v_lshl_add_u64 v[128:129], v[130:131], 0, v[166:167]
	v_lshlrev_b64 v[154:155], 2, v[158:159]
	v_lshl_add_u64 v[164:165], v[128:129], 0, v[154:155]
	v_lshl_add_u64 v[156:157], vcc, 0, v[154:155]
	global_load_dwordx4 v[132:135], v[164:165], off
	global_load_dwordx4 v[214:217], v[164:165], off offset:128
	global_load_dwordx4 v[128:131], v[156:157], off
	s_mov_b32 s62, 0x3fd744fd
	s_and_b64 vcc, exec, s[2:3]
	v_lshl_add_u64 v[152:153], s[66:67], 0, v[154:155]
	v_lshl_add_u64 v[154:155], s[42:43], 0, v[154:155]
	s_cbranch_vccnz .LBB0_811
	global_load_dwordx4 v[180:183], v[152:153], off
	global_load_dwordx4 v[184:187], v[154:155], off
	s_waitcnt vmcnt(0)
	v_sub_f32_e32 v135, v135, v162
	v_sub_f32_e32 v134, v134, v162
	v_sub_f32_e32 v133, v133, v162
	v_sub_f32_e32 v132, v132, v162
	v_pk_mul_f32 v[132:133], v[162:163], v[132:133] op_sel:[1,0]
	v_pk_mul_f32 v[134:135], v[162:163], v[134:135] op_sel:[1,0]
	v_pk_fma_f32 v[132:133], v[132:133], v[180:181], v[184:185]
	v_pk_fma_f32 v[134:135], v[134:135], v[182:183], v[186:187]

; __device__ __forceinline__ void resid_tile256(const Params& p, int l, const bf16_t* A, int lda, int nk, const bf16_t* Wt, int ldb, int goff, bool x_from_input,
;                                               const float* lng, const float* lnb, int row0, int nt256, unsigned char* lds, int tid) {
;     ...
; #pragma unroll
;     for (int m = 0; m < 8; ++m) {
;         const int lr = wr * 128 + m * 16 + fr, pp = pp0 + lr;
;         const float* xi = x_rd(p, x_from_input, b, pp);
;         float* xo = x_wr(p, b, pp);
;         float mean = 0.f, rstd = 1.f;
;         if (!x_from_input) { const size_t row = (size_t)row0 + lr; mean = stats[row * 2]; rstd = stats[row * 2 + 1]; }
; #pragma unroll
;         for (int n = 0; n < 4; ++n) {
;             const int col = nt256 * 256 + wc * 64 + n * 16 + fq * 4;
;             f32x4 xv = *(const f32x4*)(xi + col); const f32x4 g4 = *(const f32x4*)(gv + col);
;             if (!x_from_input) {
;                 const f32x4 lg = *(const f32x4*)(lng + col), lb = *(const f32x4*)(lnb + col);
; #pragma unroll
;                 for (int j = 0; j < 4; ++j) xv[j] = (xv[j] - mean) * rstd * lg[j] + lb[j];
;             }
;             f32x4 o;
; #pragma unroll
;             for (int j = 0; j < 4; ++j) o[j] = ALPHA * xv[j] + g4[j] * acc[m][n][j];
;             *(f32x4*)(xo + col) = o;
;         }
.LBB0_813:
	s_waitcnt vmcnt(1)
	v_pk_mul_f32 v[130:131], v[130:131], s[62:63] op_sel_hi:[1,0]
	v_pk_mul_f32 v[128:129], v[128:129], s[62:63] op_sel_hi:[1,0]
	s_waitcnt vmcnt(0)
	v_pk_fma_f32 v[122:123], v[122:123], v[126:127], v[130:131]
	v_pk_fma_f32 v[120:121], v[120:121], v[124:125], v[128:129]
	global_store_dwordx4 v[132:133], v[120:123], off offset:64
	v_mov_b32_e32 v124, v214
	v_mov_b32_e32 v125, v215
	v_mov_b32_e32 v126, v216
	v_mov_b32_e32 v127, v217
	s_nop 0
	global_load_dwordx4 v[120:123], v[156:157], off offset:128
	s_and_b64 vcc, exec, s[2:3]
	s_cbranch_vccnz .LBB0_815
	global_load_dwordx4 v[128:131], v[152:153], off offset:128
	global_load_dwordx4 v[180:183], v[154:155], off offset:128
	s_waitcnt vmcnt(3)
	v_sub_f32_e32 v127, v127, v162
	v_sub_f32_e32 v126, v126, v162
	v_sub_f32_e32 v125, v125, v162
	v_sub_f32_e32 v124, v124, v162
	v_pk_mul_f32 v[124:125], v[162:163], v[124:125] op_sel:[1,0]
	v_pk_mul_f32 v[126:127], v[162:163], v[126:127] op_sel:[1,0]
	s_waitcnt vmcnt(0)
	v_pk_fma_f32 v[124:125], v[124:125], v[128:129], v[180:181]
	v_pk_fma_f32 v[126:127], v[126:127], v[130:131], v[182:183]

; __device__ __forceinline__ void resid_tile256(const Params& p, int l, const bf16_t* A, int lda, int nk, const bf16_t* Wt, int ldb, int goff, bool x_from_input,
;                                               const float* lng, const float* lnb, int row0, int nt256, unsigned char* lds, int tid) {
;     ...
; #pragma unroll
;     for (int m = 0; m < 8; ++m) {
;         const int lr = wr * 128 + m * 16 + fr, pp = pp0 + lr;
;         const float* xi = x_rd(p, x_from_input, b, pp);
;         float* xo = x_wr(p, b, pp);
;         float mean = 0.f, rstd = 1.f;
;         if (!x_from_input) { const size_t row = (size_t)row0 + lr; mean = stats[row * 2]; rstd = stats[row * 2 + 1]; }
; #pragma unroll
;         for (int n = 0; n < 4; ++n) {
;             const int col = nt256 * 256 + wc * 64 + n * 16 + fq * 4;
;             f32x4 xv = *(const f32x4*)(xi + col); const f32x4 g4 = *(const f32x4*)(gv + col);
;             if (!x_from_input) {
;                 const f32x4 lg = *(const f32x4*)(lng + col), lb = *(const f32x4*)(lnb + col);
; #pragma unroll
;                 for (int j = 0; j < 4; ++j) xv[j] = (xv[j] - mean) * rstd * lg[j] + lb[j];
;             }
;             f32x4 o;
; #pragma unroll
;             for (int j = 0; j < 4; ++j) o[j] = ALPHA * xv[j] + g4[j] * acc[m][n][j];
;             *(f32x4*)(xo + col) = o;
;         }
.LBB0_820:
	v_add_u32_e32 v112, s78, v138
	v_add_u32_e32 v114, 0xffffff00, v112
	v_cmp_gt_i32_e64 s[4:5], s88, v112
	v_ashrrev_i32_e32 v113, 31, v112
	v_mov_b32_e32 v115, s86
	v_cndmask_b32_e64 v112, v114, v112, s[4:5]
	v_mov_b32_e32 v114, s81
	v_cndmask_b32_e64 v113, 0, v113, s[4:5]
	v_cndmask_b32_e64 v115, v114, v115, s[4:5]
	v_mov_b32_e32 v114, s79
	v_mov_b32_e32 v116, s80
	v_cndmask_b32_e64 v114, v114, v116, s[4:5]
	v_lshlrev_b64 v[124:125], 12, v[112:113]
	v_lshl_add_u64 v[112:113], v[114:115], 0, v[124:125]
	v_lshl_add_u64 v[122:123], v[158:159], 2, v[112:113]
	global_load_dwordx4 v[116:119], v[122:123], off
	global_load_dwordx4 v[214:217], v[122:123], off offset:128
	global_load_dwordx4 v[112:115], v[156:157], off
	s_and_b64 vcc, exec, s[2:3]
	s_cbranch_vccnz .LBB0_822
	global_load_dwordx4 v[126:129], v[152:153], off
	global_load_dwordx4 v[130:133], v[154:155], off
	s_waitcnt vmcnt(3)
	v_sub_f32_e32 v119, v119, v120
	v_sub_f32_e32 v118, v118, v120
	v_sub_f32_e32 v117, v117, v120
	v_sub_f32_e32 v116, v116, v120
	v_pk_mul_f32 v[116:117], v[120:121], v[116:117] op_sel:[1,0]
	v_pk_mul_f32 v[118:119], v[120:121], v[118:119] op_sel:[1,0]
	s_waitcnt vmcnt(0)
	v_pk_fma_f32 v[116:117], v[116:117], v[126:127], v[130:131]
	v_pk_fma_f32 v[118:119], v[118:119], v[128:129], v[132:133]

; __device__ __forceinline__ void resid_tile256(const Params& p, int l, const bf16_t* A, int lda, int nk, const bf16_t* Wt, int ldb, int goff, bool x_from_input,
;                                               const float* lng, const float* lnb, int row0, int nt256, unsigned char* lds, int tid) {
;     ...
; #pragma unroll
;     for (int m = 0; m < 8; ++m) {
;         const int lr = wr * 128 + m * 16 + fr, pp = pp0 + lr;
;         const float* xi = x_rd(p, x_from_input, b, pp);
;         float* xo = x_wr(p, b, pp);
;         float mean = 0.f, rstd = 1.f;
;         if (!x_from_input) { const size_t row = (size_t)row0 + lr; mean = stats[row * 2]; rstd = stats[row * 2 + 1]; }
; #pragma unroll
;         for (int n = 0; n < 4; ++n) {
;             const int col = nt256 * 256 + wc * 64 + n * 16 + fq * 4;
;             f32x4 xv = *(const f32x4*)(xi + col); const f32x4 g4 = *(const f32x4*)(gv + col);
;             if (!x_from_input) {
;                 const f32x4 lg = *(const f32x4*)(lng + col), lb = *(const f32x4*)(lnb + col);
; #pragma unroll
;                 for (int j = 0; j < 4; ++j) xv[j] = (xv[j] - mean) * rstd * lg[j] + lb[j];
;             }
;             f32x4 o;
; #pragma unroll
;             for (int j = 0; j < 4; ++j) o[j] = ALPHA * xv[j] + g4[j] * acc[m][n][j];
;             *(f32x4*)(xo + col) = o;
;         }
.LBB0_824:
	s_waitcnt vmcnt(1)
	v_pk_mul_f32 v[114:115], v[114:115], s[62:63] op_sel_hi:[1,0]
	v_pk_mul_f32 v[112:113], v[112:113], s[62:63] op_sel_hi:[1,0]
	s_waitcnt vmcnt(0)
	v_pk_fma_f32 v[106:107], v[106:107], v[110:111], v[114:115]
	v_pk_fma_f32 v[104:105], v[104:105], v[108:109], v[112:113]
	global_store_dwordx4 v[116:117], v[104:107], off offset:64
	v_mov_b32_e32 v108, v214
	v_mov_b32_e32 v109, v215
	v_mov_b32_e32 v110, v216
	v_mov_b32_e32 v111, v217
	s_nop 0
	global_load_dwordx4 v[104:107], v[156:157], off offset:128
	s_and_b64 vcc, exec, s[2:3]
	s_cbranch_vccnz .LBB0_826
	global_load_dwordx4 v[112:115], v[152:153], off offset:128
	global_load_dwordx4 v[124:127], v[154:155], off offset:128
	s_waitcnt vmcnt(3)
	v_sub_f32_e32 v111, v111, v120
	v_sub_f32_e32 v110, v110, v120
	v_sub_f32_e32 v109, v109, v120
	v_sub_f32_e32 v108, v108, v120
	v_pk_mul_f32 v[108:109], v[120:121], v[108:109] op_sel:[1,0]
	v_pk_mul_f32 v[110:111], v[120:121], v[110:111] op_sel:[1,0]
	s_waitcnt vmcnt(0)
	v_pk_fma_f32 v[108:109], v[108:109], v[112:113], v[124:125]
	v_pk_fma_f32 v[110:111], v[110:111], v[114:115], v[126:127]

; __device__ __forceinline__ void resid_tile256(const Params& p, int l, const bf16_t* A, int lda, int nk, const bf16_t* Wt, int ldb, int goff, bool x_from_input,
;                                               const float* lng, const float* lnb, int row0, int nt256, unsigned char* lds, int tid) {
;     ...
; #pragma unroll
;     for (int m = 0; m < 8; ++m) {
;         const int lr = wr * 128 + m * 16 + fr, pp = pp0 + lr;
;         const float* xi = x_rd(p, x_from_input, b, pp);
;         float* xo = x_wr(p, b, pp);
;         float mean = 0.f, rstd = 1.f;
;         if (!x_from_input) { const size_t row = (size_t)row0 + lr; mean = stats[row * 2]; rstd = stats[row * 2 + 1]; }
; #pragma unroll
;         for (int n = 0; n < 4; ++n) {
;             const int col = nt256 * 256 + wc * 64 + n * 16 + fq * 4;
;             f32x4 xv = *(const f32x4*)(xi + col); const f32x4 g4 = *(const f32x4*)(gv + col);
;             if (!x_from_input) {
;                 const f32x4 lg = *(const f32x4*)(lng + col), lb = *(const f32x4*)(lnb + col);
; #pragma unroll
;                 for (int j = 0; j < 4; ++j) xv[j] = (xv[j] - mean) * rstd * lg[j] + lb[j];
;             }
;             f32x4 o;
; #pragma unroll
;             for (int j = 0; j < 4; ++j) o[j] = ALPHA * xv[j] + g4[j] * acc[m][n][j];
;             *(f32x4*)(xo + col) = o;
;         }
.LBB0_831:
	v_add_u32_e32 v96, s78, v140
	v_add_u32_e32 v98, 0xffffff00, v96
	v_cmp_gt_i32_e64 s[4:5], s88, v96
	v_ashrrev_i32_e32 v97, 31, v96
	v_mov_b32_e32 v99, s86
	v_cndmask_b32_e64 v96, v98, v96, s[4:5]
	v_mov_b32_e32 v98, s81
	v_cndmask_b32_e64 v97, 0, v97, s[4:5]
	v_cndmask_b32_e64 v99, v98, v99, s[4:5]
	v_mov_b32_e32 v98, s79
	v_mov_b32_e32 v100, s80
	v_cndmask_b32_e64 v98, v98, v100, s[4:5]
	v_lshlrev_b64 v[108:109], 12, v[96:97]
	v_lshl_add_u64 v[96:97], v[98:99], 0, v[108:109]
	v_lshl_add_u64 v[106:107], v[158:159], 2, v[96:97]
	global_load_dwordx4 v[100:103], v[106:107], off
	global_load_dwordx4 v[214:217], v[106:107], off offset:128
	global_load_dwordx4 v[96:99], v[156:157], off
	s_and_b64 vcc, exec, s[2:3]
	s_cbranch_vccnz .LBB0_833
	global_load_dwordx4 v[110:113], v[152:153], off
	global_load_dwordx4 v[114:117], v[154:155], off
	s_waitcnt vmcnt(3)
	v_sub_f32_e32 v103, v103, v104
	v_sub_f32_e32 v102, v102, v104
	v_sub_f32_e32 v101, v101, v104
	v_sub_f32_e32 v100, v100, v104
	v_pk_mul_f32 v[100:101], v[104:105], v[100:101] op_sel:[1,0]
	v_pk_mul_f32 v[102:103], v[104:105], v[102:103] op_sel:[1,0]
	s_waitcnt vmcnt(0)
	v_pk_fma_f32 v[100:101], v[100:101], v[110:111], v[114:115]
	v_pk_fma_f32 v[102:103], v[102:103], v[112:113], v[116:117]

; __device__ __forceinline__ void resid_tile256(const Params& p, int l, const bf16_t* A, int lda, int nk, const bf16_t* Wt, int ldb, int goff, bool x_from_input,
;                                               const float* lng, const float* lnb, int row0, int nt256, unsigned char* lds, int tid) {
;     ...
; #pragma unroll
;     for (int m = 0; m < 8; ++m) {
;         const int lr = wr * 128 + m * 16 + fr, pp = pp0 + lr;
;         const float* xi = x_rd(p, x_from_input, b, pp);
;         float* xo = x_wr(p, b, pp);
;         float mean = 0.f, rstd = 1.f;
;         if (!x_from_input) { const size_t row = (size_t)row0 + lr; mean = stats[row * 2]; rstd = stats[row * 2 + 1]; }
; #pragma unroll
;         for (int n = 0; n < 4; ++n) {
;             const int col = nt256 * 256 + wc * 64 + n * 16 + fq * 4;
;             f32x4 xv = *(const f32x4*)(xi + col); const f32x4 g4 = *(const f32x4*)(gv + col);
;             if (!x_from_input) {
;                 const f32x4 lg = *(const f32x4*)(lng + col), lb = *(const f32x4*)(lnb + col);
; #pragma unroll
;                 for (int j = 0; j < 4; ++j) xv[j] = (xv[j] - mean) * rstd * lg[j] + lb[j];
;             }
;             f32x4 o;
; #pragma unroll
;             for (int j = 0; j < 4; ++j) o[j] = ALPHA * xv[j] + g4[j] * acc[m][n][j];
;             *(f32x4*)(xo + col) = o;
;         }
.LBB0_835:
	s_waitcnt vmcnt(1)
	v_pk_mul_f32 v[98:99], v[98:99], s[62:63] op_sel_hi:[1,0]
	v_pk_mul_f32 v[96:97], v[96:97], s[62:63] op_sel_hi:[1,0]
	s_waitcnt vmcnt(0)
	v_pk_fma_f32 v[90:91], v[90:91], v[94:95], v[98:99]
	v_pk_fma_f32 v[88:89], v[88:89], v[92:93], v[96:97]
	global_store_dwordx4 v[100:101], v[88:91], off offset:64
	v_mov_b32_e32 v92, v214
	v_mov_b32_e32 v93, v215
	v_mov_b32_e32 v94, v216
	v_mov_b32_e32 v95, v217
	s_nop 0
	global_load_dwordx4 v[88:91], v[156:157], off offset:128
	s_and_b64 vcc, exec, s[2:3]
	s_cbranch_vccnz .LBB0_837
	global_load_dwordx4 v[96:99], v[152:153], off offset:128
	global_load_dwordx4 v[108:111], v[154:155], off offset:128
	s_waitcnt vmcnt(3)
	v_sub_f32_e32 v95, v95, v104
	v_sub_f32_e32 v94, v94, v104
	v_sub_f32_e32 v93, v93, v104
	v_sub_f32_e32 v92, v92, v104
	v_pk_mul_f32 v[92:93], v[104:105], v[92:93] op_sel:[1,0]
	v_pk_mul_f32 v[94:95], v[104:105], v[94:95] op_sel:[1,0]
	s_waitcnt vmcnt(0)
	v_pk_fma_f32 v[92:93], v[92:93], v[96:97], v[108:109]
	v_pk_fma_f32 v[94:95], v[94:95], v[98:99], v[110:111]

; __device__ __forceinline__ void resid_tile256(const Params& p, int l, const bf16_t* A, int lda, int nk, const bf16_t* Wt, int ldb, int goff, bool x_from_input,
;                                               const float* lng, const float* lnb, int row0, int nt256, unsigned char* lds, int tid) {
;     ...
; #pragma unroll
;     for (int m = 0; m < 8; ++m) {
;         const int lr = wr * 128 + m * 16 + fr, pp = pp0 + lr;
;         const float* xi = x_rd(p, x_from_input, b, pp);
;         float* xo = x_wr(p, b, pp);
;         float mean = 0.f, rstd = 1.f;
;         if (!x_from_input) { const size_t row = (size_t)row0 + lr; mean = stats[row * 2]; rstd = stats[row * 2 + 1]; }
; #pragma unroll
;         for (int n = 0; n < 4; ++n) {
;             const int col = nt256 * 256 + wc * 64 + n * 16 + fq * 4;
;             f32x4 xv = *(const f32x4*)(xi + col); const f32x4 g4 = *(const f32x4*)(gv + col);
;             if (!x_from_input) {
;                 const f32x4 lg = *(const f32x4*)(lng + col), lb = *(const f32x4*)(lnb + col);
; #pragma unroll
;                 for (int j = 0; j < 4; ++j) xv[j] = (xv[j] - mean) * rstd * lg[j] + lb[j];
;             }
;             f32x4 o;
; #pragma unroll
;             for (int j = 0; j < 4; ++j) o[j] = ALPHA * xv[j] + g4[j] * acc[m][n][j];
;             *(f32x4*)(xo + col) = o;
;         }
.LBB0_842:
	v_add_u32_e32 v80, s78, v142
	v_add_u32_e32 v82, 0xffffff00, v80
	v_cmp_gt_i32_e64 s[4:5], s88, v80
	v_ashrrev_i32_e32 v81, 31, v80
	v_mov_b32_e32 v83, s86
	v_cndmask_b32_e64 v80, v82, v80, s[4:5]
	v_mov_b32_e32 v82, s81
	v_cndmask_b32_e64 v81, 0, v81, s[4:5]
	v_cndmask_b32_e64 v83, v82, v83, s[4:5]
	v_mov_b32_e32 v82, s79
	v_mov_b32_e32 v84, s80
	v_cndmask_b32_e64 v82, v82, v84, s[4:5]
	v_lshlrev_b64 v[92:93], 12, v[80:81]
	v_lshl_add_u64 v[80:81], v[82:83], 0, v[92:93]
	v_lshl_add_u64 v[90:91], v[158:159], 2, v[80:81]
	global_load_dwordx4 v[84:87], v[90:91], off
	global_load_dwordx4 v[214:217], v[90:91], off offset:128
	global_load_dwordx4 v[80:83], v[156:157], off
	s_and_b64 vcc, exec, s[2:3]
	s_cbranch_vccnz .LBB0_844
	global_load_dwordx4 v[94:97], v[152:153], off
	global_load_dwordx4 v[98:101], v[154:155], off
	s_waitcnt vmcnt(3)
	v_sub_f32_e32 v87, v87, v88
	v_sub_f32_e32 v86, v86, v88
	v_sub_f32_e32 v85, v85, v88
	v_sub_f32_e32 v84, v84, v88
	v_pk_mul_f32 v[84:85], v[88:89], v[84:85] op_sel:[1,0]
	v_pk_mul_f32 v[86:87], v[88:89], v[86:87] op_sel:[1,0]
	s_waitcnt vmcnt(0)
	v_pk_fma_f32 v[84:85], v[84:85], v[94:95], v[98:99]
	v_pk_fma_f32 v[86:87], v[86:87], v[96:97], v[100:101]

; __device__ __forceinline__ void resid_tile256(const Params& p, int l, const bf16_t* A, int lda, int nk, const bf16_t* Wt, int ldb, int goff, bool x_from_input,
;                                               const float* lng, const float* lnb, int row0, int nt256, unsigned char* lds, int tid) {
;     ...
; #pragma unroll
;     for (int m = 0; m < 8; ++m) {
;         const int lr = wr * 128 + m * 16 + fr, pp = pp0 + lr;
;         const float* xi = x_rd(p, x_from_input, b, pp);
;         float* xo = x_wr(p, b, pp);
;         float mean = 0.f, rstd = 1.f;
;         if (!x_from_input) { const size_t row = (size_t)row0 + lr; mean = stats[row * 2]; rstd = stats[row * 2 + 1]; }
; #pragma unroll
;         for (int n = 0; n < 4; ++n) {
;             const int col = nt256 * 256 + wc * 64 + n * 16 + fq * 4;
;             f32x4 xv = *(const f32x4*)(xi + col); const f32x4 g4 = *(const f32x4*)(gv + col);
;             if (!x_from_input) {
;                 const f32x4 lg = *(const f32x4*)(lng + col), lb = *(const f32x4*)(lnb + col);
; #pragma unroll
;                 for (int j = 0; j < 4; ++j) xv[j] = (xv[j] - mean) * rstd * lg[j] + lb[j];
;             }
;             f32x4 o;
; #pragma unroll
;             for (int j = 0; j < 4; ++j) o[j] = ALPHA * xv[j] + g4[j] * acc[m][n][j];
;             *(f32x4*)(xo + col) = o;
;         }
.LBB0_846:
	s_waitcnt vmcnt(1)
	v_pk_mul_f32 v[82:83], v[82:83], s[62:63] op_sel_hi:[1,0]
	v_pk_mul_f32 v[80:81], v[80:81], s[62:63] op_sel_hi:[1,0]
	s_waitcnt vmcnt(0)
	v_pk_fma_f32 v[74:75], v[74:75], v[78:79], v[82:83]
	v_pk_fma_f32 v[72:73], v[72:73], v[76:77], v[80:81]
	global_store_dwordx4 v[84:85], v[72:75], off offset:64
	v_mov_b32_e32 v76, v214
	v_mov_b32_e32 v77, v215
	v_mov_b32_e32 v78, v216
	v_mov_b32_e32 v79, v217
	s_nop 0
	global_load_dwordx4 v[72:75], v[156:157], off offset:128
	s_and_b64 vcc, exec, s[2:3]
	s_cbranch_vccnz .LBB0_848
	global_load_dwordx4 v[80:83], v[152:153], off offset:128
	global_load_dwordx4 v[92:95], v[154:155], off offset:128
	s_waitcnt vmcnt(3)
	v_sub_f32_e32 v79, v79, v88
	v_sub_f32_e32 v78, v78, v88
	v_sub_f32_e32 v77, v77, v88
	v_sub_f32_e32 v76, v76, v88
	v_pk_mul_f32 v[76:77], v[88:89], v[76:77] op_sel:[1,0]
	v_pk_mul_f32 v[78:79], v[88:89], v[78:79] op_sel:[1,0]
	s_waitcnt vmcnt(0)
	v_pk_fma_f32 v[76:77], v[76:77], v[80:81], v[92:93]
	v_pk_fma_f32 v[78:79], v[78:79], v[82:83], v[94:95]

; __device__ __forceinline__ void resid_tile256(const Params& p, int l, const bf16_t* A, int lda, int nk, const bf16_t* Wt, int ldb, int goff, bool x_from_input,
;                                               const float* lng, const float* lnb, int row0, int nt256, unsigned char* lds, int tid) {
;     ...
; #pragma unroll
;     for (int m = 0; m < 8; ++m) {
;         const int lr = wr * 128 + m * 16 + fr, pp = pp0 + lr;
;         const float* xi = x_rd(p, x_from_input, b, pp);
;         float* xo = x_wr(p, b, pp);
;         float mean = 0.f, rstd = 1.f;
;         if (!x_from_input) { const size_t row = (size_t)row0 + lr; mean = stats[row * 2]; rstd = stats[row * 2 + 1]; }
; #pragma unroll
;         for (int n = 0; n < 4; ++n) {
;             const int col = nt256 * 256 + wc * 64 + n * 16 + fq * 4;
;             f32x4 xv = *(const f32x4*)(xi + col); const f32x4 g4 = *(const f32x4*)(gv + col);
;             if (!x_from_input) {
;                 const f32x4 lg = *(const f32x4*)(lng + col), lb = *(const f32x4*)(lnb + col);
; #pragma unroll
;                 for (int j = 0; j < 4; ++j) xv[j] = (xv[j] - mean) * rstd * lg[j] + lb[j];
;             }
;             f32x4 o;
; #pragma unroll
;             for (int j = 0; j < 4; ++j) o[j] = ALPHA * xv[j] + g4[j] * acc[m][n][j];
;             *(f32x4*)(xo + col) = o;
;         }
.LBB0_853:
	v_add_u32_e32 v64, s78, v144
	v_add_u32_e32 v66, 0xffffff00, v64
	v_cmp_gt_i32_e64 s[4:5], s88, v64
	v_ashrrev_i32_e32 v65, 31, v64
	v_mov_b32_e32 v67, s86
	v_cndmask_b32_e64 v64, v66, v64, s[4:5]
	v_mov_b32_e32 v66, s81
	v_cndmask_b32_e64 v65, 0, v65, s[4:5]
	v_cndmask_b32_e64 v67, v66, v67, s[4:5]
	v_mov_b32_e32 v66, s79
	v_mov_b32_e32 v68, s80
	v_cndmask_b32_e64 v66, v66, v68, s[4:5]
	v_lshlrev_b64 v[76:77], 12, v[64:65]
	v_lshl_add_u64 v[64:65], v[66:67], 0, v[76:77]
	v_lshl_add_u64 v[74:75], v[158:159], 2, v[64:65]
	global_load_dwordx4 v[68:71], v[74:75], off
	global_load_dwordx4 v[214:217], v[74:75], off offset:128
	global_load_dwordx4 v[64:67], v[156:157], off
	s_and_b64 vcc, exec, s[2:3]
	s_cbranch_vccnz .LBB0_855
	global_load_dwordx4 v[78:81], v[152:153], off
	global_load_dwordx4 v[82:85], v[154:155], off
	s_waitcnt vmcnt(3)
	v_sub_f32_e32 v71, v71, v72
	v_sub_f32_e32 v70, v70, v72
	v_sub_f32_e32 v69, v69, v72
	v_sub_f32_e32 v68, v68, v72
	v_pk_mul_f32 v[68:69], v[72:73], v[68:69] op_sel:[1,0]
	v_pk_mul_f32 v[70:71], v[72:73], v[70:71] op_sel:[1,0]
	s_waitcnt vmcnt(0)
	v_pk_fma_f32 v[68:69], v[68:69], v[78:79], v[82:83]
	v_pk_fma_f32 v[70:71], v[70:71], v[80:81], v[84:85]

; __device__ __forceinline__ void resid_tile256(const Params& p, int l, const bf16_t* A, int lda, int nk, const bf16_t* Wt, int ldb, int goff, bool x_from_input,
;                                               const float* lng, const float* lnb, int row0, int nt256, unsigned char* lds, int tid) {
;     ...
; #pragma unroll
;     for (int m = 0; m < 8; ++m) {
;         const int lr = wr * 128 + m * 16 + fr, pp = pp0 + lr;
;         const float* xi = x_rd(p, x_from_input, b, pp);
;         float* xo = x_wr(p, b, pp);
;         float mean = 0.f, rstd = 1.f;
;         if (!x_from_input) { const size_t row = (size_t)row0 + lr; mean = stats[row * 2]; rstd = stats[row * 2 + 1]; }
; #pragma unroll
;         for (int n = 0; n < 4; ++n) {
;             const int col = nt256 * 256 + wc * 64 + n * 16 + fq * 4;
;             f32x4 xv = *(const f32x4*)(xi + col); const f32x4 g4 = *(const f32x4*)(gv + col);
;             if (!x_from_input) {
;                 const f32x4 lg = *(const f32x4*)(lng + col), lb = *(const f32x4*)(lnb + col);
; #pragma unroll
;                 for (int j = 0; j < 4; ++j) xv[j] = (xv[j] - mean) * rstd * lg[j] + lb[j];
;             }
;             f32x4 o;
; #pragma unroll
;             for (int j = 0; j < 4; ++j) o[j] = ALPHA * xv[j] + g4[j] * acc[m][n][j];
;             *(f32x4*)(xo + col) = o;
;         }
.LBB0_857:
	s_waitcnt vmcnt(1)
	v_pk_mul_f32 v[66:67], v[66:67], s[62:63] op_sel_hi:[1,0]
	v_pk_mul_f32 v[64:65], v[64:65], s[62:63] op_sel_hi:[1,0]
	s_waitcnt vmcnt(0)
	v_pk_fma_f32 v[58:59], v[58:59], v[62:63], v[66:67]
	v_pk_fma_f32 v[56:57], v[56:57], v[60:61], v[64:65]
	global_store_dwordx4 v[68:69], v[56:59], off offset:64
	v_mov_b32_e32 v60, v214
	v_mov_b32_e32 v61, v215
	v_mov_b32_e32 v62, v216
	v_mov_b32_e32 v63, v217
	s_nop 0
	global_load_dwordx4 v[56:59], v[156:157], off offset:128
	s_and_b64 vcc, exec, s[2:3]
	s_cbranch_vccnz .LBB0_859
	global_load_dwordx4 v[64:67], v[152:153], off offset:128
	global_load_dwordx4 v[76:79], v[154:155], off offset:128
	s_waitcnt vmcnt(3)
	v_sub_f32_e32 v63, v63, v72
	v_sub_f32_e32 v62, v62, v72
	v_sub_f32_e32 v61, v61, v72
	v_sub_f32_e32 v60, v60, v72
	v_pk_mul_f32 v[60:61], v[72:73], v[60:61] op_sel:[1,0]
	v_pk_mul_f32 v[62:63], v[72:73], v[62:63] op_sel:[1,0]
	s_waitcnt vmcnt(0)
	v_pk_fma_f32 v[60:61], v[60:61], v[64:65], v[76:77]
	v_pk_fma_f32 v[62:63], v[62:63], v[66:67], v[78:79]

; __device__ __forceinline__ void resid_tile256(const Params& p, int l, const bf16_t* A, int lda, int nk, const bf16_t* Wt, int ldb, int goff, bool x_from_input,
;                                               const float* lng, const float* lnb, int row0, int nt256, unsigned char* lds, int tid) {
;     ...
; #pragma unroll
;     for (int m = 0; m < 8; ++m) {
;         const int lr = wr * 128 + m * 16 + fr, pp = pp0 + lr;
;         const float* xi = x_rd(p, x_from_input, b, pp);
;         float* xo = x_wr(p, b, pp);
;         float mean = 0.f, rstd = 1.f;
;         if (!x_from_input) { const size_t row = (size_t)row0 + lr; mean = stats[row * 2]; rstd = stats[row * 2 + 1]; }
; #pragma unroll
;         for (int n = 0; n < 4; ++n) {
;             const int col = nt256 * 256 + wc * 64 + n * 16 + fq * 4;
;             f32x4 xv = *(const f32x4*)(xi + col); const f32x4 g4 = *(const f32x4*)(gv + col);
;             if (!x_from_input) {
;                 const f32x4 lg = *(const f32x4*)(lng + col), lb = *(const f32x4*)(lnb + col);
; #pragma unroll
;                 for (int j = 0; j < 4; ++j) xv[j] = (xv[j] - mean) * rstd * lg[j] + lb[j];
;             }
;             f32x4 o;
; #pragma unroll
;             for (int j = 0; j < 4; ++j) o[j] = ALPHA * xv[j] + g4[j] * acc[m][n][j];
;             *(f32x4*)(xo + col) = o;
;         }
.LBB0_864:
	v_add_u32_e32 v48, s78, v146
	v_add_u32_e32 v50, 0xffffff00, v48
	v_cmp_gt_i32_e64 s[4:5], s88, v48
	v_ashrrev_i32_e32 v49, 31, v48
	v_mov_b32_e32 v51, s86
	v_cndmask_b32_e64 v48, v50, v48, s[4:5]
	v_mov_b32_e32 v50, s81
	v_cndmask_b32_e64 v49, 0, v49, s[4:5]
	v_cndmask_b32_e64 v51, v50, v51, s[4:5]
	v_mov_b32_e32 v50, s79
	v_mov_b32_e32 v52, s80
	v_cndmask_b32_e64 v50, v50, v52, s[4:5]
	v_lshlrev_b64 v[60:61], 12, v[48:49]
	v_lshl_add_u64 v[48:49], v[50:51], 0, v[60:61]
	v_lshl_add_u64 v[58:59], v[158:159], 2, v[48:49]
	global_load_dwordx4 v[52:55], v[58:59], off
	global_load_dwordx4 v[214:217], v[58:59], off offset:128
	global_load_dwordx4 v[48:51], v[156:157], off
	s_and_b64 vcc, exec, s[2:3]
	s_cbranch_vccnz .LBB0_866
	global_load_dwordx4 v[62:65], v[152:153], off
	global_load_dwordx4 v[66:69], v[154:155], off
	s_waitcnt vmcnt(3)
	v_sub_f32_e32 v55, v55, v56
	v_sub_f32_e32 v54, v54, v56
	v_sub_f32_e32 v53, v53, v56
	v_sub_f32_e32 v52, v52, v56
	v_pk_mul_f32 v[52:53], v[56:57], v[52:53] op_sel:[1,0]
	v_pk_mul_f32 v[54:55], v[56:57], v[54:55] op_sel:[1,0]
	s_waitcnt vmcnt(0)
	v_pk_fma_f32 v[52:53], v[52:53], v[62:63], v[66:67]
	v_pk_fma_f32 v[54:55], v[54:55], v[64:65], v[68:69]

; __device__ __forceinline__ void resid_tile256(const Params& p, int l, const bf16_t* A, int lda, int nk, const bf16_t* Wt, int ldb, int goff, bool x_from_input,
;                                               const float* lng, const float* lnb, int row0, int nt256, unsigned char* lds, int tid) {
;     ...
; #pragma unroll
;     for (int m = 0; m < 8; ++m) {
;         const int lr = wr * 128 + m * 16 + fr, pp = pp0 + lr;
;         const float* xi = x_rd(p, x_from_input, b, pp);
;         float* xo = x_wr(p, b, pp);
;         float mean = 0.f, rstd = 1.f;
;         if (!x_from_input) { const size_t row = (size_t)row0 + lr; mean = stats[row * 2]; rstd = stats[row * 2 + 1]; }
; #pragma unroll
;         for (int n = 0; n < 4; ++n) {
;             const int col = nt256 * 256 + wc * 64 + n * 16 + fq * 4;
;             f32x4 xv = *(const f32x4*)(xi + col); const f32x4 g4 = *(const f32x4*)(gv + col);
;             if (!x_from_input) {
;                 const f32x4 lg = *(const f32x4*)(lng + col), lb = *(const f32x4*)(lnb + col);
; #pragma unroll
;                 for (int j = 0; j < 4; ++j) xv[j] = (xv[j] - mean) * rstd * lg[j] + lb[j];
;             }
;             f32x4 o;
; #pragma unroll
;             for (int j = 0; j < 4; ++j) o[j] = ALPHA * xv[j] + g4[j] * acc[m][n][j];
;             *(f32x4*)(xo + col) = o;
;         }
.LBB0_868:
	s_waitcnt vmcnt(1)
	v_pk_mul_f32 v[50:51], v[50:51], s[62:63] op_sel_hi:[1,0]
	v_pk_mul_f32 v[48:49], v[48:49], s[62:63] op_sel_hi:[1,0]
	s_waitcnt vmcnt(0)
	v_pk_fma_f32 v[42:43], v[42:43], v[46:47], v[50:51]
	v_pk_fma_f32 v[40:41], v[40:41], v[44:45], v[48:49]
	global_store_dwordx4 v[52:53], v[40:43], off offset:64
	v_mov_b32_e32 v44, v214
	v_mov_b32_e32 v45, v215
	v_mov_b32_e32 v46, v216
	v_mov_b32_e32 v47, v217
	s_nop 0
	global_load_dwordx4 v[40:43], v[156:157], off offset:128
	s_and_b64 vcc, exec, s[2:3]
	s_cbranch_vccnz .LBB0_870
	global_load_dwordx4 v[48:51], v[152:153], off offset:128
	global_load_dwordx4 v[60:63], v[154:155], off offset:128
	s_waitcnt vmcnt(3)
	v_sub_f32_e32 v47, v47, v56
	v_sub_f32_e32 v46, v46, v56
	v_sub_f32_e32 v45, v45, v56
	v_sub_f32_e32 v44, v44, v56
	v_pk_mul_f32 v[44:45], v[56:57], v[44:45] op_sel:[1,0]
	v_pk_mul_f32 v[46:47], v[56:57], v[46:47] op_sel:[1,0]
	s_waitcnt vmcnt(0)
	v_pk_fma_f32 v[44:45], v[44:45], v[48:49], v[60:61]
	v_pk_fma_f32 v[46:47], v[46:47], v[50:51], v[62:63]

; __device__ __forceinline__ void resid_tile256(const Params& p, int l, const bf16_t* A, int lda, int nk, const bf16_t* Wt, int ldb, int goff, bool x_from_input,
;                                               const float* lng, const float* lnb, int row0, int nt256, unsigned char* lds, int tid) {
;     ...
; #pragma unroll
;     for (int m = 0; m < 8; ++m) {
;         const int lr = wr * 128 + m * 16 + fr, pp = pp0 + lr;
;         const float* xi = x_rd(p, x_from_input, b, pp);
;         float* xo = x_wr(p, b, pp);
;         float mean = 0.f, rstd = 1.f;
;         if (!x_from_input) { const size_t row = (size_t)row0 + lr; mean = stats[row * 2]; rstd = stats[row * 2 + 1]; }
; #pragma unroll
;         for (int n = 0; n < 4; ++n) {
;             const int col = nt256 * 256 + wc * 64 + n * 16 + fq * 4;
;             f32x4 xv = *(const f32x4*)(xi + col); const f32x4 g4 = *(const f32x4*)(gv + col);
;             if (!x_from_input) {
;                 const f32x4 lg = *(const f32x4*)(lng + col), lb = *(const f32x4*)(lnb + col);
; #pragma unroll
;                 for (int j = 0; j < 4; ++j) xv[j] = (xv[j] - mean) * rstd * lg[j] + lb[j];
;             }
;             f32x4 o;
; #pragma unroll
;             for (int j = 0; j < 4; ++j) o[j] = ALPHA * xv[j] + g4[j] * acc[m][n][j];
;             *(f32x4*)(xo + col) = o;
;         }
.LBB0_875:
	v_add_u32_e32 v32, s78, v148
	v_add_u32_e32 v34, 0xffffff00, v32
	v_cmp_gt_i32_e64 s[4:5], s88, v32
	v_ashrrev_i32_e32 v33, 31, v32
	v_mov_b32_e32 v35, s86
	v_cndmask_b32_e64 v32, v34, v32, s[4:5]
	v_mov_b32_e32 v34, s81
	v_cndmask_b32_e64 v33, 0, v33, s[4:5]
	v_cndmask_b32_e64 v35, v34, v35, s[4:5]
	v_mov_b32_e32 v34, s79
	v_mov_b32_e32 v36, s80
	v_cndmask_b32_e64 v34, v34, v36, s[4:5]
	v_lshlrev_b64 v[44:45], 12, v[32:33]
	v_lshl_add_u64 v[32:33], v[34:35], 0, v[44:45]
	v_lshl_add_u64 v[42:43], v[158:159], 2, v[32:33]
	global_load_dwordx4 v[36:39], v[42:43], off
	global_load_dwordx4 v[214:217], v[42:43], off offset:128
	global_load_dwordx4 v[32:35], v[156:157], off
	s_and_b64 vcc, exec, s[2:3]
	s_cbranch_vccnz .LBB0_877
	global_load_dwordx4 v[46:49], v[152:153], off
	global_load_dwordx4 v[50:53], v[154:155], off
	s_waitcnt vmcnt(3)
	v_sub_f32_e32 v39, v39, v40
	v_sub_f32_e32 v38, v38, v40
	v_sub_f32_e32 v37, v37, v40
	v_sub_f32_e32 v36, v36, v40
	v_pk_mul_f32 v[36:37], v[40:41], v[36:37] op_sel:[1,0]
	v_pk_mul_f32 v[38:39], v[40:41], v[38:39] op_sel:[1,0]
	s_waitcnt vmcnt(0)
	v_pk_fma_f32 v[36:37], v[36:37], v[46:47], v[50:51]
	v_pk_fma_f32 v[38:39], v[38:39], v[48:49], v[52:53]

; __device__ __forceinline__ void resid_tile256(const Params& p, int l, const bf16_t* A, int lda, int nk, const bf16_t* Wt, int ldb, int goff, bool x_from_input,
;                                               const float* lng, const float* lnb, int row0, int nt256, unsigned char* lds, int tid) {
;     ...
; #pragma unroll
;     for (int m = 0; m < 8; ++m) {
;         const int lr = wr * 128 + m * 16 + fr, pp = pp0 + lr;
;         const float* xi = x_rd(p, x_from_input, b, pp);
;         float* xo = x_wr(p, b, pp);
;         float mean = 0.f, rstd = 1.f;
;         if (!x_from_input) { const size_t row = (size_t)row0 + lr; mean = stats[row * 2]; rstd = stats[row * 2 + 1]; }
; #pragma unroll
;         for (int n = 0; n < 4; ++n) {
;             const int col = nt256 * 256 + wc * 64 + n * 16 + fq * 4;
;             f32x4 xv = *(const f32x4*)(xi + col); const f32x4 g4 = *(const f32x4*)(gv + col);
;             if (!x_from_input) {
;                 const f32x4 lg = *(const f32x4*)(lng + col), lb = *(const f32x4*)(lnb + col);
; #pragma unroll
;                 for (int j = 0; j < 4; ++j) xv[j] = (xv[j] - mean) * rstd * lg[j] + lb[j];
;             }
;             f32x4 o;
; #pragma unroll
;             for (int j = 0; j < 4; ++j) o[j] = ALPHA * xv[j] + g4[j] * acc[m][n][j];
;             *(f32x4*)(xo + col) = o;
;         }
.LBB0_879:
	s_waitcnt vmcnt(1)
	v_pk_mul_f32 v[34:35], v[34:35], s[62:63] op_sel_hi:[1,0]
	v_pk_mul_f32 v[32:33], v[32:33], s[62:63] op_sel_hi:[1,0]
	s_waitcnt vmcnt(0)
	v_pk_fma_f32 v[26:27], v[26:27], v[30:31], v[34:35]
	v_pk_fma_f32 v[24:25], v[24:25], v[28:29], v[32:33]
	global_store_dwordx4 v[36:37], v[24:27], off offset:64
	v_mov_b32_e32 v28, v214
	v_mov_b32_e32 v29, v215
	v_mov_b32_e32 v30, v216
	v_mov_b32_e32 v31, v217
	s_nop 0
	global_load_dwordx4 v[24:27], v[156:157], off offset:128
	s_and_b64 vcc, exec, s[2:3]
	s_cbranch_vccnz .LBB0_881
	global_load_dwordx4 v[32:35], v[152:153], off offset:128
	global_load_dwordx4 v[44:47], v[154:155], off offset:128
	s_waitcnt vmcnt(3)
	v_sub_f32_e32 v31, v31, v40
	v_sub_f32_e32 v30, v30, v40
	v_sub_f32_e32 v29, v29, v40
	v_sub_f32_e32 v28, v28, v40
	v_pk_mul_f32 v[28:29], v[40:41], v[28:29] op_sel:[1,0]
	v_pk_mul_f32 v[30:31], v[40:41], v[30:31] op_sel:[1,0]
	s_waitcnt vmcnt(0)
	v_pk_fma_f32 v[28:29], v[28:29], v[32:33], v[44:45]
	v_pk_fma_f32 v[30:31], v[30:31], v[34:35], v[46:47]

; __device__ __forceinline__ void resid_tile256(const Params& p, int l, const bf16_t* A, int lda, int nk, const bf16_t* Wt, int ldb, int goff, bool x_from_input,
;                                               const float* lng, const float* lnb, int row0, int nt256, unsigned char* lds, int tid) {
;     ...
; #pragma unroll
;     for (int m = 0; m < 8; ++m) {
;         const int lr = wr * 128 + m * 16 + fr, pp = pp0 + lr;
;         const float* xi = x_rd(p, x_from_input, b, pp);
;         float* xo = x_wr(p, b, pp);
;         float mean = 0.f, rstd = 1.f;
;         if (!x_from_input) { const size_t row = (size_t)row0 + lr; mean = stats[row * 2]; rstd = stats[row * 2 + 1]; }
; #pragma unroll
;         for (int n = 0; n < 4; ++n) {
;             const int col = nt256 * 256 + wc * 64 + n * 16 + fq * 4;
;             f32x4 xv = *(const f32x4*)(xi + col); const f32x4 g4 = *(const f32x4*)(gv + col);
;             if (!x_from_input) {
;                 const f32x4 lg = *(const f32x4*)(lng + col), lb = *(const f32x4*)(lnb + col);
; #pragma unroll
;                 for (int j = 0; j < 4; ++j) xv[j] = (xv[j] - mean) * rstd * lg[j] + lb[j];
;             }
;             f32x4 o;
; #pragma unroll
;             for (int j = 0; j < 4; ++j) o[j] = ALPHA * xv[j] + g4[j] * acc[m][n][j];
;             *(f32x4*)(xo + col) = o;
;         }
.LBB0_886:
	v_add_u32_e32 v16, s78, v150
	v_add_u32_e32 v18, 0xffffff00, v16
	v_cmp_gt_i32_e64 s[4:5], s88, v16
	v_ashrrev_i32_e32 v17, 31, v16
	v_mov_b32_e32 v19, s86
	v_cndmask_b32_e64 v16, v18, v16, s[4:5]
	v_mov_b32_e32 v18, s81
	v_cndmask_b32_e64 v17, 0, v17, s[4:5]
	v_cndmask_b32_e64 v19, v18, v19, s[4:5]
	v_mov_b32_e32 v18, s79
	v_mov_b32_e32 v20, s80
	v_cndmask_b32_e64 v18, v18, v20, s[4:5]
	v_lshlrev_b64 v[28:29], 12, v[16:17]
	v_lshl_add_u64 v[16:17], v[18:19], 0, v[28:29]
	v_lshl_add_u64 v[26:27], v[158:159], 2, v[16:17]
	global_load_dwordx4 v[20:23], v[26:27], off
	global_load_dwordx4 v[214:217], v[26:27], off offset:128
	global_load_dwordx4 v[16:19], v[156:157], off
	s_and_b64 vcc, exec, s[2:3]
	s_cbranch_vccnz .LBB0_888
	global_load_dwordx4 v[30:33], v[152:153], off
	global_load_dwordx4 v[34:37], v[154:155], off
	s_waitcnt vmcnt(3)
	v_sub_f32_e32 v23, v23, v24
	v_sub_f32_e32 v22, v22, v24
	v_sub_f32_e32 v21, v21, v24
	v_sub_f32_e32 v20, v20, v24
	v_pk_mul_f32 v[20:21], v[24:25], v[20:21] op_sel:[1,0]
	v_pk_mul_f32 v[22:23], v[24:25], v[22:23] op_sel:[1,0]
	s_waitcnt vmcnt(0)
	v_pk_fma_f32 v[20:21], v[20:21], v[30:31], v[34:35]
	v_pk_fma_f32 v[22:23], v[22:23], v[32:33], v[36:37]

; __device__ __forceinline__ void resid_tile256(const Params& p, int l, const bf16_t* A, int lda, int nk, const bf16_t* Wt, int ldb, int goff, bool x_from_input,
;                                               const float* lng, const float* lnb, int row0, int nt256, unsigned char* lds, int tid) {
;     ...
; #pragma unroll
;     for (int m = 0; m < 8; ++m) {
;         const int lr = wr * 128 + m * 16 + fr, pp = pp0 + lr;
;         const float* xi = x_rd(p, x_from_input, b, pp);
;         float* xo = x_wr(p, b, pp);
;         float mean = 0.f, rstd = 1.f;
;         if (!x_from_input) { const size_t row = (size_t)row0 + lr; mean = stats[row * 2]; rstd = stats[row * 2 + 1]; }
; #pragma unroll
;         for (int n = 0; n < 4; ++n) {
;             const int col = nt256 * 256 + wc * 64 + n * 16 + fq * 4;
;             f32x4 xv = *(const f32x4*)(xi + col); const f32x4 g4 = *(const f32x4*)(gv + col);
;             if (!x_from_input) {
;                 const f32x4 lg = *(const f32x4*)(lng + col), lb = *(const f32x4*)(lnb + col);
; #pragma unroll
;                 for (int j = 0; j < 4; ++j) xv[j] = (xv[j] - mean) * rstd * lg[j] + lb[j];
;             }
;             f32x4 o;
; #pragma unroll
;             for (int j = 0; j < 4; ++j) o[j] = ALPHA * xv[j] + g4[j] * acc[m][n][j];
;             *(f32x4*)(xo + col) = o;
;         }
.LBB0_890:
	s_waitcnt vmcnt(1)
	v_pk_mul_f32 v[18:19], v[18:19], s[62:63] op_sel_hi:[1,0]
	v_pk_mul_f32 v[16:17], v[16:17], s[62:63] op_sel_hi:[1,0]
	s_waitcnt vmcnt(0)
	v_pk_fma_f32 v[6:7], v[6:7], v[14:15], v[18:19]
	v_pk_fma_f32 v[4:5], v[4:5], v[12:13], v[16:17]
	global_store_dwordx4 v[20:21], v[4:7], off offset:64
	v_mov_b32_e32 v12, v214
	v_mov_b32_e32 v13, v215
	v_mov_b32_e32 v14, v216
	v_mov_b32_e32 v15, v217
	s_nop 0
	global_load_dwordx4 v[4:7], v[156:157], off offset:128
	s_and_b64 vcc, exec, s[2:3]
	s_cbranch_vccnz .LBB0_892
	global_load_dwordx4 v[16:19], v[152:153], off offset:128
	global_load_dwordx4 v[28:31], v[154:155], off offset:128
	s_waitcnt vmcnt(3)
	v_sub_f32_e32 v15, v15, v24
	v_sub_f32_e32 v14, v14, v24
	v_sub_f32_e32 v13, v13, v24
	v_sub_f32_e32 v12, v12, v24
	v_pk_mul_f32 v[12:13], v[24:25], v[12:13] op_sel:[1,0]
	v_pk_mul_f32 v[14:15], v[24:25], v[14:15] op_sel:[1,0]
	s_waitcnt vmcnt(0)
	v_pk_fma_f32 v[12:13], v[12:13], v[16:17], v[28:29]
	v_pk_fma_f32 v[14:15], v[14:15], v[18:19], v[30:31]

; template <int MT>
; __device__ __forceinline__ void resid_tile(const Params& p, int l, const bf16_t* A, int lda, int nk, const bf16_t* Wt, int ldb, int goff, bool x_from_input,
;                                            const float* lng, const float* lnb, int row0, int nt, unsigned char* lds, int tid) {
;     ...
; #pragma unroll
;     for (int m = 0; m < MT; ++m) {
;         const int lr = wr * 16 * MT + m * 16 + fr, pp = pp0 + lr;
;         const float* xi = x_rd(p, x_from_input, b, pp);
;         float* xo = x_wr(p, b, pp);
;         float mean = 0.f, rstd = 1.f;
;         if (!x_from_input) { const size_t row = (size_t)row0 + lr; mean = stats[row * 2]; rstd = stats[row * 2 + 1]; }
; #pragma unroll
;         for (int n = 0; n < 4; ++n) {
;             const int col = nt * 128 + wc * 64 + n * 16 + fq * 4;
;             f32x4 xv = *(const f32x4*)(xi + col); const f32x4 g4 = *(const f32x4*)(gv + col);
;             if (!x_from_input) {
;                 const f32x4 lg = *(const f32x4*)(lng + col), lb = *(const f32x4*)(lnb + col);
; #pragma unroll
;                 for (int j = 0; j < 4; ++j) xv[j] = (xv[j] - mean) * rstd * lg[j] + lb[j];
;             }
;             f32x4 o;
; #pragma unroll
;             for (int j = 0; j < 4; ++j) o[j] = ALPHA * xv[j] + g4[j] * acc[m][n][j];
;             *(f32x4*)(xo + col) = o;
;         }
.LBB0_962:
	v_readlane_b32 s4, v254, 60
	s_add_u32 s4, s69, s4
	s_addc_u32 s5, s68, 0
	s_mulk_i32 s5, 0x6000
	s_mul_hi_u32 s28, s4, 0x6000
	s_add_i32 s28, s28, s5
	s_mulk_i32 s4, 0x6000
	v_lshlrev_b64 v[32:33], 12, v[32:33]
	s_add_u32 s4, s46, s4
	v_lshl_add_u64 v[32:33], v[34:35], 0, v[32:33]
	v_and_b32_e32 v34, 64, v168
	s_addc_u32 s5, s47, s28
	v_readlane_b32 s28, v254, 61
	s_add_u32 s4, s4, 0x2534000
	s_addc_u32 s5, s5, 0
	v_or3_b32 v41, v34, v169, s28
	v_lshlrev_b32_e32 v160, 2, v41
	v_lshl_add_u64 v[46:47], v[32:33], 0, v[160:161]
	global_load_dwordx4 v[36:39], v[46:47], off
	global_load_dwordx4 v[214:217], v[46:47], off offset:128
	global_load_dwordx4 v[32:35], v160, s[4:5]
	s_and_b64 vcc, exec, s[2:3]
	s_cbranch_vccnz .LBB0_964
	global_load_dwordx4 v[50:53], v160, s[66:67]
	global_load_dwordx4 v[54:57], v160, s[42:43]
	s_waitcnt vmcnt(0)
	v_sub_f32_e32 v39, v39, v44
	v_sub_f32_e32 v38, v38, v44
	v_sub_f32_e32 v37, v37, v44
	v_sub_f32_e32 v36, v36, v44
	v_pk_mul_f32 v[36:37], v[44:45], v[36:37] op_sel:[1,0]
	v_pk_mul_f32 v[38:39], v[44:45], v[38:39] op_sel:[1,0]
	v_pk_fma_f32 v[36:37], v[36:37], v[50:51], v[54:55]
	v_pk_fma_f32 v[38:39], v[38:39], v[52:53], v[56:57]

; template <int MT>
; __device__ __forceinline__ void resid_tile(const Params& p, int l, const bf16_t* A, int lda, int nk, const bf16_t* Wt, int ldb, int goff, bool x_from_input,
;                                            const float* lng, const float* lnb, int row0, int nt, unsigned char* lds, int tid) {
;     ...
; #pragma unroll
;     for (int m = 0; m < MT; ++m) {
;         const int lr = wr * 16 * MT + m * 16 + fr, pp = pp0 + lr;
;         const float* xi = x_rd(p, x_from_input, b, pp);
;         float* xo = x_wr(p, b, pp);
;         float mean = 0.f, rstd = 1.f;
;         if (!x_from_input) { const size_t row = (size_t)row0 + lr; mean = stats[row * 2]; rstd = stats[row * 2 + 1]; }
; #pragma unroll
;         for (int n = 0; n < 4; ++n) {
;             const int col = nt * 128 + wc * 64 + n * 16 + fq * 4;
;             f32x4 xv = *(const f32x4*)(xi + col); const f32x4 g4 = *(const f32x4*)(gv + col);
;             if (!x_from_input) {
;                 const f32x4 lg = *(const f32x4*)(lng + col), lb = *(const f32x4*)(lnb + col);
; #pragma unroll
;                 for (int j = 0; j < 4; ++j) xv[j] = (xv[j] - mean) * rstd * lg[j] + lb[j];
;             }
;             f32x4 o;
; #pragma unroll
;             for (int j = 0; j < 4; ++j) o[j] = ALPHA * xv[j] + g4[j] * acc[m][n][j];
;             *(f32x4*)(xo + col) = o;
;         }
.LBB0_966:
	s_waitcnt vmcnt(1)
	v_pk_mul_f32 v[34:35], v[34:35], s[62:63] op_sel_hi:[1,0]
	v_pk_mul_f32 v[32:33], v[32:33], s[62:63] op_sel_hi:[1,0]
	s_waitcnt vmcnt(0)
	v_pk_fma_f32 v[26:27], v[26:27], v[30:31], v[34:35]
	v_pk_fma_f32 v[24:25], v[24:25], v[28:29], v[32:33]
	global_store_dwordx4 v[38:39], v[24:27], off offset:64
	v_mov_b32_e32 v28, v214
	v_mov_b32_e32 v29, v215
	v_mov_b32_e32 v30, v216
	v_mov_b32_e32 v31, v217
	s_and_b64 vcc, exec, s[2:3]
	v_mov_b32_e32 v24, 0x80
	v_lshl_or_b32 v32, v41, 2, v24
	global_load_dwordx4 v[24:27], v32, s[4:5]
	s_cbranch_vccnz .LBB0_968
	global_load_dwordx4 v[48:51], v160, s[66:67] offset:128
	global_load_dwordx4 v[52:55], v160, s[42:43] offset:128
	s_waitcnt vmcnt(3)
	v_sub_f32_e32 v31, v31, v44
	v_sub_f32_e32 v30, v30, v44
	v_sub_f32_e32 v29, v29, v44
	v_sub_f32_e32 v28, v28, v44
	v_pk_mul_f32 v[28:29], v[44:45], v[28:29] op_sel:[1,0]
	v_pk_mul_f32 v[30:31], v[44:45], v[30:31] op_sel:[1,0]
	s_waitcnt vmcnt(0)
	v_pk_fma_f32 v[28:29], v[28:29], v[48:49], v[52:53]
	v_pk_fma_f32 v[30:31], v[30:31], v[50:51], v[54:55]

; template <int MT>
; __device__ __forceinline__ void resid_tile(const Params& p, int l, const bf16_t* A, int lda, int nk, const bf16_t* Wt, int ldb, int goff, bool x_from_input,
;                                            const float* lng, const float* lnb, int row0, int nt, unsigned char* lds, int tid) {
;     ...
; #pragma unroll
;     for (int m = 0; m < MT; ++m) {
;         const int lr = wr * 16 * MT + m * 16 + fr, pp = pp0 + lr;
;         const float* xi = x_rd(p, x_from_input, b, pp);
;         float* xo = x_wr(p, b, pp);
;         float mean = 0.f, rstd = 1.f;
;         if (!x_from_input) { const size_t row = (size_t)row0 + lr; mean = stats[row * 2]; rstd = stats[row * 2 + 1]; }
; #pragma unroll
;         for (int n = 0; n < 4; ++n) {
;             const int col = nt * 128 + wc * 64 + n * 16 + fq * 4;
;             f32x4 xv = *(const f32x4*)(xi + col); const f32x4 g4 = *(const f32x4*)(gv + col);
;             if (!x_from_input) {
;                 const f32x4 lg = *(const f32x4*)(lng + col), lb = *(const f32x4*)(lnb + col);
; #pragma unroll
;                 for (int j = 0; j < 4; ++j) xv[j] = (xv[j] - mean) * rstd * lg[j] + lb[j];
;             }
;             f32x4 o;
; #pragma unroll
;             for (int j = 0; j < 4; ++j) o[j] = ALPHA * xv[j] + g4[j] * acc[m][n][j];
;             *(f32x4*)(xo + col) = o;
;         }
.LBB0_981:
	v_lshlrev_b64 v[18:19], 12, v[20:21]
	v_lshl_add_u64 v[18:19], v[22:23], 0, v[18:19]
	v_lshl_add_u64 v[16:17], s[4:5], 0, v[160:161]
	v_lshl_add_u64 v[30:31], v[18:19], 0, v[160:161]
	global_load_dwordx4 v[20:23], v[30:31], off
	global_load_dwordx4 v[214:217], v[30:31], off offset:128
	s_nop 0
	global_load_dwordx4 v[16:19], v[16:17], off
	s_and_b64 vcc, exec, s[2:3]
	s_cbranch_vccnz .LBB0_983
	global_load_dwordx4 v[38:41], v160, s[66:67]
	global_load_dwordx4 v[42:45], v160, s[42:43]
	s_waitcnt vmcnt(3)
	v_sub_f32_e32 v23, v23, v26
	v_sub_f32_e32 v22, v22, v26
	v_sub_f32_e32 v21, v21, v26
	v_sub_f32_e32 v20, v20, v26
	v_pk_mul_f32 v[20:21], v[26:27], v[20:21] op_sel:[1,0]
	v_pk_mul_f32 v[22:23], v[26:27], v[22:23] op_sel:[1,0]
	s_waitcnt vmcnt(0)
	v_pk_fma_f32 v[20:21], v[20:21], v[38:39], v[42:43]
	v_pk_fma_f32 v[22:23], v[22:23], v[40:41], v[44:45]

; template <int MT>
; __device__ __forceinline__ void resid_tile(const Params& p, int l, const bf16_t* A, int lda, int nk, const bf16_t* Wt, int ldb, int goff, bool x_from_input,
;                                            const float* lng, const float* lnb, int row0, int nt, unsigned char* lds, int tid) {
;     ...
; #pragma unroll
;     for (int m = 0; m < MT; ++m) {
;         const int lr = wr * 16 * MT + m * 16 + fr, pp = pp0 + lr;
;         const float* xi = x_rd(p, x_from_input, b, pp);
;         float* xo = x_wr(p, b, pp);
;         float mean = 0.f, rstd = 1.f;
;         if (!x_from_input) { const size_t row = (size_t)row0 + lr; mean = stats[row * 2]; rstd = stats[row * 2 + 1]; }
; #pragma unroll
;         for (int n = 0; n < 4; ++n) {
;             const int col = nt * 128 + wc * 64 + n * 16 + fq * 4;
;             f32x4 xv = *(const f32x4*)(xi + col); const f32x4 g4 = *(const f32x4*)(gv + col);
;             if (!x_from_input) {
;                 const f32x4 lg = *(const f32x4*)(lng + col), lb = *(const f32x4*)(lnb + col);
; #pragma unroll
;                 for (int j = 0; j < 4; ++j) xv[j] = (xv[j] - mean) * rstd * lg[j] + lb[j];
;             }
;             f32x4 o;
; #pragma unroll
;             for (int j = 0; j < 4; ++j) o[j] = ALPHA * xv[j] + g4[j] * acc[m][n][j];
;             *(f32x4*)(xo + col) = o;
;         }
.LBB0_985:
	s_waitcnt vmcnt(1)
	v_pk_mul_f32 v[18:19], v[18:19], s[62:63] op_sel_hi:[1,0]
	v_pk_mul_f32 v[16:17], v[16:17], s[62:63] op_sel_hi:[1,0]
	s_waitcnt vmcnt(0)
	v_pk_fma_f32 v[10:11], v[10:11], v[14:15], v[18:19]
	v_pk_fma_f32 v[8:9], v[8:9], v[12:13], v[16:17]
	v_mov_b32_e32 v33, v161
	global_store_dwordx4 v[20:21], v[8:11], off offset:64
	v_lshl_add_u64 v[22:23], s[4:5], 0, v[32:33]
	v_mov_b32_e32 v12, v214
	v_mov_b32_e32 v13, v215
	v_mov_b32_e32 v14, v216
	v_mov_b32_e32 v15, v217
	global_load_dwordx4 v[8:11], v[22:23], off
	s_and_b64 vcc, exec, s[2:3]
	s_cbranch_vccnz .LBB0_987
	global_load_dwordx4 v[16:19], v160, s[66:67] offset:128
	global_load_dwordx4 v[22:25], v160, s[42:43] offset:128
	s_waitcnt vmcnt(3)
	v_sub_f32_e32 v15, v15, v26
	v_sub_f32_e32 v14, v14, v26
	v_sub_f32_e32 v13, v13, v26
	v_sub_f32_e32 v12, v12, v26
	v_pk_mul_f32 v[12:13], v[26:27], v[12:13] op_sel:[1,0]
	v_pk_mul_f32 v[14:15], v[26:27], v[14:15] op_sel:[1,0]
	s_waitcnt vmcnt(0)
	v_pk_fma_f32 v[12:13], v[12:13], v[16:17], v[22:23]
	v_pk_fma_f32 v[14:15], v[14:15], v[18:19], v[24:25]

; __device__ __forceinline__ void resid_tile256(const Params& p, int l, const bf16_t* A, int lda, int nk, const bf16_t* Wt, int ldb, int goff, bool x_from_input,
;                                               const float* lng, const float* lnb, int row0, int nt256, unsigned char* lds, int tid) {
;     ...
; #pragma unroll
;     for (int m = 0; m < 8; ++m) {
;         const int lr = wr * 128 + m * 16 + fr, pp = pp0 + lr;
;         const float* xi = x_rd(p, x_from_input, b, pp);
;         float* xo = x_wr(p, b, pp);
;         float mean = 0.f, rstd = 1.f;
;         if (!x_from_input) { const size_t row = (size_t)row0 + lr; mean = stats[row * 2]; rstd = stats[row * 2 + 1]; }
; #pragma unroll
;         for (int n = 0; n < 4; ++n) {
;             const int col = nt256 * 256 + wc * 64 + n * 16 + fq * 4;
;             f32x4 xv = *(const f32x4*)(xi + col); const f32x4 g4 = *(const f32x4*)(gv + col);
;             if (!x_from_input) {
;                 const f32x4 lg = *(const f32x4*)(lng + col), lb = *(const f32x4*)(lnb + col);
; #pragma unroll
;                 for (int j = 0; j < 4; ++j) xv[j] = (xv[j] - mean) * rstd * lg[j] + lb[j];
;             }
;             f32x4 o;
; #pragma unroll
;             for (int j = 0; j < 4; ++j) o[j] = ALPHA * xv[j] + g4[j] * acc[m][n][j];
;             *(f32x4*)(xo + col) = o;
;         }
.LBB0_1074:
	s_mul_hi_i32 s2, s48, 0x38e38e39
	s_lshr_b32 s3, s2, 31
	s_ashr_i32 s2, s2, 9
	s_add_i32 s2, s2, s3
	s_mulk_i32 s2, 0x900
	s_sub_i32 s71, s48, s2
	s_cmpk_gt_i32 s71, 0xff
	s_cselect_b32 s2, s50, 16
	s_ashr_i32 s3, s2, 31
	s_add_u32 s2, s39, s2
	s_addc_u32 s3, s28, s3
	s_mulk_i32 s3, 0x6000
	s_mul_hi_u32 s75, s2, 0x6000
	s_add_i32 s75, s75, s3
	s_mulk_i32 s2, 0x6000
	s_add_u32 s2, s52, s2
	s_addc_u32 s3, s54, s75
	v_lshl_or_b32 v128, s51, 8, v176
	s_ashr_i32 s51, s50, 31
	s_lshl_b64 s[76:77], s[50:51], 23
	s_lshl_b64 s[50:51], s[50:51], 20
	s_add_u32 s75, s18, s76
	s_addc_u32 s76, s21, s77
	v_add_u32_e32 v129, s71, v132
	s_add_u32 s50, s56, s50
	v_add_u32_e32 v130, 0xffffff00, v129
	v_ashrrev_i32_e32 v131, 31, v129
	s_addc_u32 s51, s57, s51
	v_cmp_gt_i32_e32 vcc, s88, v129
	v_mov_b32_e32 v152, s76
	v_mov_b32_e32 v153, s51
	v_cndmask_b32_e32 v131, 0, v131, vcc
	v_cndmask_b32_e32 v130, v130, v129, vcc
	v_mov_b32_e32 v154, s75
	v_mov_b32_e32 v155, s50
	v_cndmask_b32_e32 v149, v152, v153, vcc
	v_cndmask_b32_e32 v148, v154, v155, vcc
	v_lshlrev_b64 v[130:131], 12, v[130:131]
	v_ashrrev_i32_e32 v129, 31, v128
	v_lshl_add_u64 v[130:131], v[148:149], 0, v[130:131]
	v_lshl_add_u64 v[148:149], s[48:49], 0, v[132:133]
	v_lshlrev_b64 v[150:151], 2, v[128:129]
	v_lshl_add_u64 v[148:149], v[148:149], 3, s[46:47]
	v_lshl_add_u64 v[192:193], v[130:131], 0, v[150:151]
	global_load_dwordx2 v[190:191], v[148:149], off
	global_load_dwordx4 v[156:159], v[192:193], off
	global_load_dwordx4 v[214:217], v[192:193], off offset:128
	v_lshl_add_u64 v[128:129], s[4:5], 0, v[150:151]
	v_lshl_add_u64 v[130:131], s[6:7], 0, v[150:151]
	global_load_dwordx4 v[162:165], v[128:129], off
	global_load_dwordx4 v[178:181], v[130:131], off
	v_lshl_add_u64 v[148:149], s[2:3], 0, v[150:151]
	global_load_dwordx4 v[182:185], v[148:149], off
	global_load_dwordx4 v[186:189], v[192:193], off offset:64
	s_mov_b32 s2, 0x3fd744fd
	s_mov_b64 s[90:91], 0x20000
	s_waitcnt vmcnt(0)
	v_sub_f32_e32 v159, v159, v190
	v_sub_f32_e32 v158, v158, v190
	v_sub_f32_e32 v157, v157, v190
	v_sub_f32_e32 v156, v156, v190
	v_pk_mul_f32 v[156:157], v[190:191], v[156:157] op_sel:[1,0]
	v_pk_mul_f32 v[158:159], v[190:191], v[158:159] op_sel:[1,0]
	v_pk_fma_f32 v[156:157], v[156:157], v[162:163], v[178:179]
	v_pk_fma_f32 v[158:159], v[158:159], v[164:165], v[180:181]
	v_pk_mul_f32 v[156:157], v[156:157], s[2:3] op_sel_hi:[1,0]
	v_pk_mul_f32 v[158:159], v[158:159], s[2:3] op_sel_hi:[1,0]
	v_pk_fma_f32 v[124:125], v[124:125], v[182:183], v[156:157]
	v_pk_fma_f32 v[126:127], v[126:127], v[184:185], v[158:159]
	global_store_dwordx4 v[192:193], v[124:127], off
	global_load_dwordx4 v[124:127], v[128:129], off offset:64
	s_nop 0
	global_load_dwordx4 v[156:159], v[130:131], off offset:64
	global_load_dwordx4 v[162:165], v[148:149], off offset:64
	v_mov_b32_e32 v178, v214
	v_mov_b32_e32 v179, v215
	v_mov_b32_e32 v180, v216
	v_mov_b32_e32 v181, v217
	v_sub_f32_e32 v183, v189, v190
	v_sub_f32_e32 v182, v188, v190
	v_sub_f32_e32 v185, v187, v190
	v_sub_f32_e32 v184, v186, v190
	v_pk_mul_f32 v[184:185], v[190:191], v[184:185] op_sel:[1,0]
	v_pk_mul_f32 v[182:183], v[190:191], v[182:183] op_sel:[1,0]
	s_waitcnt vmcnt(1)
	v_pk_fma_f32 v[124:125], v[184:185], v[124:125], v[156:157]
	v_pk_fma_f32 v[126:127], v[182:183], v[126:127], v[158:159]
	v_pk_mul_f32 v[124:125], v[124:125], s[2:3] op_sel_hi:[1,0]
	v_pk_mul_f32 v[126:127], v[126:127], s[2:3] op_sel_hi:[1,0]
	s_waitcnt vmcnt(0)
	v_pk_fma_f32 v[120:121], v[120:121], v[162:163], v[124:125]
	v_pk_fma_f32 v[122:123], v[122:123], v[164:165], v[126:127]
	global_store_dwordx4 v[192:193], v[120:123], off offset:64
	global_load_dwordx4 v[120:123], v[128:129], off offset:128
	s_nop 0
	global_load_dwordx4 v[124:127], v[130:131], off offset:128
	global_load_dwordx4 v[156:159], v[148:149], off offset:128
	global_load_dwordx4 v[162:165], v[192:193], off offset:192
	s_waitcnt vmcnt(5)
	v_sub_f32_e32 v181, v181, v190
	v_sub_f32_e32 v180, v180, v190
	v_sub_f32_e32 v179, v179, v190
	v_sub_f32_e32 v178, v178, v190
	v_pk_mul_f32 v[178:179], v[190:191], v[178:179] op_sel:[1,0]
	v_pk_mul_f32 v[180:181], v[190:191], v[180:181] op_sel:[1,0]
	s_waitcnt vmcnt(2)
	v_pk_fma_f32 v[120:121], v[178:179], v[120:121], v[124:125]
	v_pk_fma_f32 v[122:123], v[180:181], v[122:123], v[126:127]
	v_pk_mul_f32 v[120:121], v[120:121], s[2:3] op_sel_hi:[1,0]
	v_pk_mul_f32 v[122:123], v[122:123], s[2:3] op_sel_hi:[1,0]
	s_waitcnt vmcnt(1)
	v_pk_fma_f32 v[116:117], v[116:117], v[156:157], v[120:121]
	v_pk_fma_f32 v[118:119], v[118:119], v[158:159], v[122:123]
	global_store_dwordx4 v[192:193], v[116:119], off offset:128
	global_load_dwordx4 v[116:119], v[128:129], off offset:192
	s_nop 0
	global_load_dwordx4 v[120:123], v[130:131], off offset:192
	global_load_dwordx4 v[124:127], v[148:149], off offset:192
	v_add_u32_e32 v158, s71, v134
	v_add_u32_e32 v160, 0xffffff00, v158
	v_ashrrev_i32_e32 v159, 31, v158
	v_cmp_gt_i32_e32 vcc, s88, v158
	s_waitcnt vmcnt(4)
	v_sub_f32_e32 v163, v163, v190
	v_sub_f32_e32 v162, v162, v190
	v_cndmask_b32_e32 v159, 0, v159, vcc
	v_cndmask_b32_e32 v158, v160, v158, vcc
	v_lshlrev_b64 v[158:159], 12, v[158:159]
	v_cndmask_b32_e32 v178, v154, v155, vcc
	v_cndmask_b32_e32 v179, v152, v153, vcc
	v_lshl_add_u64 v[158:159], v[178:179], 0, v[158:159]
	v_lshl_add_u64 v[178:179], v[158:159], 0, v[150:151]
	v_sub_f32_e32 v159, v165, v190
	v_sub_f32_e32 v158, v164, v190
	v_pk_mul_f32 v[162:163], v[190:191], v[162:163] op_sel:[1,0]
	v_pk_mul_f32 v[158:159], v[190:191], v[158:159] op_sel:[1,0]
	v_lshl_add_u64 v[156:157], s[48:49], 0, v[134:135]
	v_lshl_add_u64 v[156:157], v[156:157], 3, s[46:47]
	s_waitcnt vmcnt(1)
; __device__ __forceinline__ void resid_tile256(const Params& p, int l, const bf16_t* A, int lda, int nk, const bf16_t* Wt, int ldb, int goff, bool x_from_input,
;                                               const float* lng, const float* lnb, int row0, int nt256, unsigned char* lds, int tid) {
;     ...
; #pragma unroll
;     for (int m = 0; m < 8; ++m) {
;         const int lr = wr * 128 + m * 16 + fr, pp = pp0 + lr;
;         const float* xi = x_rd(p, x_from_input, b, pp);
;         float* xo = x_wr(p, b, pp);
;         float mean = 0.f, rstd = 1.f;
;         if (!x_from_input) { const size_t row = (size_t)row0 + lr; mean = stats[row * 2]; rstd = stats[row * 2 + 1]; }
; #pragma unroll
;         for (int n = 0; n < 4; ++n) {
;             const int col = nt256 * 256 + wc * 64 + n * 16 + fq * 4;
;             f32x4 xv = *(const f32x4*)(xi + col); const f32x4 g4 = *(const f32x4*)(gv + col);
;             if (!x_from_input) {
;                 const f32x4 lg = *(const f32x4*)(lng + col), lb = *(const f32x4*)(lnb + col);
; #pragma unroll
;                 for (int j = 0; j < 4; ++j) xv[j] = (xv[j] - mean) * rstd * lg[j] + lb[j];
;             }
;             f32x4 o;
; #pragma unroll
;             for (int j = 0; j < 4; ++j) o[j] = ALPHA * xv[j] + g4[j] * acc[m][n][j];
;             *(f32x4*)(xo + col) = o;
;         }
	v_pk_fma_f32 v[118:119], v[158:159], v[118:119], v[122:123]
	v_pk_fma_f32 v[116:117], v[162:163], v[116:117], v[120:121]
	v_pk_mul_f32 v[118:119], v[118:119], s[2:3] op_sel_hi:[1,0]
	v_pk_mul_f32 v[116:117], v[116:117], s[2:3] op_sel_hi:[1,0]
	s_waitcnt vmcnt(0)
	v_pk_fma_f32 v[114:115], v[114:115], v[126:127], v[118:119]
	v_pk_fma_f32 v[112:113], v[112:113], v[124:125], v[116:117]
	global_store_dwordx4 v[192:193], v[112:115], off offset:192
	global_load_dwordx2 v[162:163], v[156:157], off
	s_nop 0
	global_load_dwordx4 v[112:115], v[178:179], off
	global_load_dwordx4 v[214:217], v[178:179], off offset:128
	global_load_dwordx4 v[116:119], v[128:129], off
	global_load_dwordx4 v[120:123], v[130:131], off
	global_load_dwordx4 v[124:127], v[148:149], off
	global_load_dwordx4 v[156:159], v[178:179], off offset:64
	s_waitcnt vmcnt(4)
	v_sub_f32_e32 v115, v115, v162
	v_sub_f32_e32 v114, v114, v162
	v_sub_f32_e32 v113, v113, v162
	v_sub_f32_e32 v112, v112, v162
	v_pk_mul_f32 v[112:113], v[162:163], v[112:113] op_sel:[1,0]
	v_pk_mul_f32 v[114:115], v[162:163], v[114:115] op_sel:[1,0]
	s_waitcnt vmcnt(2)
	v_pk_fma_f32 v[112:113], v[112:113], v[116:117], v[120:121]
	v_pk_fma_f32 v[114:115], v[114:115], v[118:119], v[122:123]
	v_pk_mul_f32 v[112:113], v[112:113], s[2:3] op_sel_hi:[1,0]
	v_pk_mul_f32 v[114:115], v[114:115], s[2:3] op_sel_hi:[1,0]
	s_waitcnt vmcnt(1)
	v_pk_fma_f32 v[108:109], v[108:109], v[124:125], v[112:113]
	v_pk_fma_f32 v[110:111], v[110:111], v[126:127], v[114:115]
	global_store_dwordx4 v[178:179], v[108:111], off
	global_load_dwordx4 v[108:111], v[128:129], off offset:64
	s_nop 0
	global_load_dwordx4 v[112:115], v[130:131], off offset:64
	global_load_dwordx4 v[116:119], v[148:149], off offset:64
	v_mov_b32_e32 v120, v214
	v_mov_b32_e32 v121, v215
	v_mov_b32_e32 v122, v216
	v_mov_b32_e32 v123, v217
	s_waitcnt vmcnt(4)
	v_sub_f32_e32 v125, v159, v162
	v_sub_f32_e32 v124, v158, v162
	v_sub_f32_e32 v127, v157, v162
	v_sub_f32_e32 v126, v156, v162
	v_pk_mul_f32 v[126:127], v[162:163], v[126:127] op_sel:[1,0]
	v_pk_mul_f32 v[124:125], v[162:163], v[124:125] op_sel:[1,0]
	s_waitcnt vmcnt(1)
	v_pk_fma_f32 v[108:109], v[126:127], v[108:109], v[112:113]
	v_pk_fma_f32 v[110:111], v[124:125], v[110:111], v[114:115]
	v_pk_mul_f32 v[108:109], v[108:109], s[2:3] op_sel_hi:[1,0]
	v_pk_mul_f32 v[110:111], v[110:111], s[2:3] op_sel_hi:[1,0]
	s_waitcnt vmcnt(0)
	v_pk_fma_f32 v[104:105], v[104:105], v[116:117], v[108:109]
	v_pk_fma_f32 v[106:107], v[106:107], v[118:119], v[110:111]
	global_store_dwordx4 v[178:179], v[104:107], off offset:64
	global_load_dwordx4 v[104:107], v[128:129], off offset:128
	s_nop 0
	global_load_dwordx4 v[108:111], v[130:131], off offset:128
	global_load_dwordx4 v[112:115], v[148:149], off offset:128
	global_load_dwordx4 v[116:119], v[178:179], off offset:192
	s_waitcnt vmcnt(5)
	v_sub_f32_e32 v123, v123, v162
	v_sub_f32_e32 v122, v122, v162
	v_sub_f32_e32 v121, v121, v162
	v_sub_f32_e32 v120, v120, v162
	v_pk_mul_f32 v[120:121], v[162:163], v[120:121] op_sel:[1,0]
	v_pk_mul_f32 v[122:123], v[162:163], v[122:123] op_sel:[1,0]
	s_waitcnt vmcnt(2)
	v_pk_fma_f32 v[104:105], v[120:121], v[104:105], v[108:109]
	v_pk_fma_f32 v[106:107], v[122:123], v[106:107], v[110:111]
	v_pk_mul_f32 v[104:105], v[104:105], s[2:3] op_sel_hi:[1,0]
	v_pk_mul_f32 v[106:107], v[106:107], s[2:3] op_sel_hi:[1,0]
	s_waitcnt vmcnt(1)
	v_pk_fma_f32 v[100:101], v[100:101], v[112:113], v[104:105]
	v_pk_fma_f32 v[102:103], v[102:103], v[114:115], v[106:107]
	global_store_dwordx4 v[178:179], v[100:103], off offset:128
	global_load_dwordx4 v[100:103], v[128:129], off offset:192
	s_nop 0
	global_load_dwordx4 v[104:107], v[130:131], off offset:192
	global_load_dwordx4 v[108:111], v[148:149], off offset:192
	v_add_u32_e32 v114, s71, v136
	v_add_u32_e32 v120, 0xffffff00, v114
	v_ashrrev_i32_e32 v115, 31, v114
	v_cmp_gt_i32_e32 vcc, s88, v114
	s_waitcnt vmcnt(4)
	v_sub_f32_e32 v117, v117, v162
	v_sub_f32_e32 v116, v116, v162
	v_cndmask_b32_e32 v115, 0, v115, vcc
	v_cndmask_b32_e32 v114, v120, v114, vcc
	v_lshlrev_b64 v[114:115], 12, v[114:115]
	v_cndmask_b32_e32 v120, v154, v155, vcc
	v_cndmask_b32_e32 v121, v152, v153, vcc
	v_lshl_add_u64 v[114:115], v[120:121], 0, v[114:115]
	v_lshl_add_u64 v[120:121], v[114:115], 0, v[150:151]
	v_sub_f32_e32 v115, v119, v162
	v_sub_f32_e32 v114, v118, v162
	v_pk_mul_f32 v[116:117], v[162:163], v[116:117] op_sel:[1,0]
	v_pk_mul_f32 v[114:115], v[162:163], v[114:115] op_sel:[1,0]
	v_lshl_add_u64 v[112:113], s[48:49], 0, v[136:137]
	v_lshl_add_u64 v[112:113], v[112:113], 3, s[46:47]
	s_waitcnt vmcnt(1)
	v_pk_fma_f32 v[102:103], v[114:115], v[102:103], v[106:107]
	v_pk_fma_f32 v[100:101], v[116:117], v[100:101], v[104:105]
	v_pk_mul_f32 v[102:103], v[102:103], s[2:3] op_sel_hi:[1,0]
	v_pk_mul_f32 v[100:101], v[100:101], s[2:3] op_sel_hi:[1,0]
	s_waitcnt vmcnt(0)
	v_pk_fma_f32 v[98:99], v[98:99], v[110:111], v[102:103]
	v_pk_fma_f32 v[96:97], v[96:97], v[108:109], v[100:101]
	global_store_dwordx4 v[178:179], v[96:99], off offset:192
	global_load_dwordx2 v[116:117], v[112:113], off
	s_nop 0
	global_load_dwordx4 v[96:99], v[120:121], off
	global_load_dwordx4 v[214:217], v[120:121], off offset:128
	global_load_dwordx4 v[100:103], v[128:129], off
	global_load_dwordx4 v[104:107], v[130:131], off
	global_load_dwordx4 v[108:111], v[148:149], off
	global_load_dwordx4 v[112:115], v[120:121], off offset:64
	s_waitcnt vmcnt(4)
	v_sub_f32_e32 v99, v99, v116
	v_sub_f32_e32 v98, v98, v116
	v_sub_f32_e32 v97, v97, v116
	v_sub_f32_e32 v96, v96, v116
	v_pk_mul_f32 v[96:97], v[116:117], v[96:97] op_sel:[1,0]
	v_pk_mul_f32 v[98:99], v[116:117], v[98:99] op_sel:[1,0]
	s_waitcnt vmcnt(2)
; __device__ __forceinline__ void resid_tile256(const Params& p, int l, const bf16_t* A, int lda, int nk, const bf16_t* Wt, int ldb, int goff, bool x_from_input,
;                                               const float* lng, const float* lnb, int row0, int nt256, unsigned char* lds, int tid) {
;     ...
; #pragma unroll
;     for (int m = 0; m < 8; ++m) {
;         const int lr = wr * 128 + m * 16 + fr, pp = pp0 + lr;
;         const float* xi = x_rd(p, x_from_input, b, pp);
;         float* xo = x_wr(p, b, pp);
;         float mean = 0.f, rstd = 1.f;
;         if (!x_from_input) { const size_t row = (size_t)row0 + lr; mean = stats[row * 2]; rstd = stats[row * 2 + 1]; }
; #pragma unroll
;         for (int n = 0; n < 4; ++n) {
;             const int col = nt256 * 256 + wc * 64 + n * 16 + fq * 4;
;             f32x4 xv = *(const f32x4*)(xi + col); const f32x4 g4 = *(const f32x4*)(gv + col);
;             if (!x_from_input) {
;                 const f32x4 lg = *(const f32x4*)(lng + col), lb = *(const f32x4*)(lnb + col);
; #pragma unroll
;                 for (int j = 0; j < 4; ++j) xv[j] = (xv[j] - mean) * rstd * lg[j] + lb[j];
;             }
;             f32x4 o;
; #pragma unroll
;             for (int j = 0; j < 4; ++j) o[j] = ALPHA * xv[j] + g4[j] * acc[m][n][j];
;             *(f32x4*)(xo + col) = o;
;         }
	v_pk_fma_f32 v[96:97], v[96:97], v[100:101], v[104:105]
	v_pk_fma_f32 v[98:99], v[98:99], v[102:103], v[106:107]
	v_pk_mul_f32 v[96:97], v[96:97], s[2:3] op_sel_hi:[1,0]
	v_pk_mul_f32 v[98:99], v[98:99], s[2:3] op_sel_hi:[1,0]
	s_waitcnt vmcnt(1)
	v_pk_fma_f32 v[92:93], v[92:93], v[108:109], v[96:97]
	v_pk_fma_f32 v[94:95], v[94:95], v[110:111], v[98:99]
	global_store_dwordx4 v[120:121], v[92:95], off
	global_load_dwordx4 v[92:95], v[128:129], off offset:64
	s_nop 0
	global_load_dwordx4 v[96:99], v[130:131], off offset:64
	global_load_dwordx4 v[100:103], v[148:149], off offset:64
	v_mov_b32_e32 v104, v214
	v_mov_b32_e32 v105, v215
	v_mov_b32_e32 v106, v216
	v_mov_b32_e32 v107, v217
	s_waitcnt vmcnt(4)
	v_sub_f32_e32 v109, v115, v116
	v_sub_f32_e32 v108, v114, v116
	v_sub_f32_e32 v111, v113, v116
	v_sub_f32_e32 v110, v112, v116
	v_pk_mul_f32 v[110:111], v[116:117], v[110:111] op_sel:[1,0]
	v_pk_mul_f32 v[108:109], v[116:117], v[108:109] op_sel:[1,0]
	s_waitcnt vmcnt(1)
	v_pk_fma_f32 v[92:93], v[110:111], v[92:93], v[96:97]
	v_pk_fma_f32 v[94:95], v[108:109], v[94:95], v[98:99]
	v_pk_mul_f32 v[92:93], v[92:93], s[2:3] op_sel_hi:[1,0]
	v_pk_mul_f32 v[94:95], v[94:95], s[2:3] op_sel_hi:[1,0]
	s_waitcnt vmcnt(0)
	v_pk_fma_f32 v[88:89], v[88:89], v[100:101], v[92:93]
	v_pk_fma_f32 v[90:91], v[90:91], v[102:103], v[94:95]
	global_store_dwordx4 v[120:121], v[88:91], off offset:64
	global_load_dwordx4 v[88:91], v[128:129], off offset:128
	s_nop 0
	global_load_dwordx4 v[92:95], v[130:131], off offset:128
	global_load_dwordx4 v[96:99], v[148:149], off offset:128
	global_load_dwordx4 v[100:103], v[120:121], off offset:192
	s_waitcnt vmcnt(5)
	v_sub_f32_e32 v107, v107, v116
	v_sub_f32_e32 v106, v106, v116
	v_sub_f32_e32 v105, v105, v116
	v_sub_f32_e32 v104, v104, v116
	v_pk_mul_f32 v[104:105], v[116:117], v[104:105] op_sel:[1,0]
	v_pk_mul_f32 v[106:107], v[116:117], v[106:107] op_sel:[1,0]
	s_waitcnt vmcnt(2)
	v_pk_fma_f32 v[88:89], v[104:105], v[88:89], v[92:93]
	v_pk_fma_f32 v[90:91], v[106:107], v[90:91], v[94:95]
	v_pk_mul_f32 v[88:89], v[88:89], s[2:3] op_sel_hi:[1,0]
	v_pk_mul_f32 v[90:91], v[90:91], s[2:3] op_sel_hi:[1,0]
	s_waitcnt vmcnt(1)
	v_pk_fma_f32 v[84:85], v[84:85], v[96:97], v[88:89]
	v_pk_fma_f32 v[86:87], v[86:87], v[98:99], v[90:91]
	global_store_dwordx4 v[120:121], v[84:87], off offset:128
	global_load_dwordx4 v[84:87], v[128:129], off offset:192
	s_nop 0
	global_load_dwordx4 v[88:91], v[130:131], off offset:192
	global_load_dwordx4 v[92:95], v[148:149], off offset:192
	v_add_u32_e32 v98, s71, v138
	v_add_u32_e32 v104, 0xffffff00, v98
	v_ashrrev_i32_e32 v99, 31, v98
	v_cmp_gt_i32_e32 vcc, s88, v98
	s_waitcnt vmcnt(4)
	v_sub_f32_e32 v101, v101, v116
	v_sub_f32_e32 v100, v100, v116
	v_cndmask_b32_e32 v99, 0, v99, vcc
	v_cndmask_b32_e32 v98, v104, v98, vcc
	v_lshlrev_b64 v[98:99], 12, v[98:99]
	v_cndmask_b32_e32 v104, v154, v155, vcc
	v_cndmask_b32_e32 v105, v152, v153, vcc
	v_lshl_add_u64 v[98:99], v[104:105], 0, v[98:99]
	v_lshl_add_u64 v[104:105], v[98:99], 0, v[150:151]
	v_sub_f32_e32 v99, v103, v116
	v_sub_f32_e32 v98, v102, v116
	v_pk_mul_f32 v[100:101], v[116:117], v[100:101] op_sel:[1,0]
	v_pk_mul_f32 v[98:99], v[116:117], v[98:99] op_sel:[1,0]
	v_lshl_add_u64 v[96:97], s[48:49], 0, v[138:139]
	v_lshl_add_u64 v[96:97], v[96:97], 3, s[46:47]
	s_waitcnt vmcnt(1)
	v_pk_fma_f32 v[86:87], v[98:99], v[86:87], v[90:91]
	v_pk_fma_f32 v[84:85], v[100:101], v[84:85], v[88:89]
	v_pk_mul_f32 v[86:87], v[86:87], s[2:3] op_sel_hi:[1,0]
	v_pk_mul_f32 v[84:85], v[84:85], s[2:3] op_sel_hi:[1,0]
	s_waitcnt vmcnt(0)
	v_pk_fma_f32 v[82:83], v[82:83], v[94:95], v[86:87]
	v_pk_fma_f32 v[80:81], v[80:81], v[92:93], v[84:85]
	global_store_dwordx4 v[120:121], v[80:83], off offset:192
	global_load_dwordx2 v[100:101], v[96:97], off
	s_nop 0
	global_load_dwordx4 v[80:83], v[104:105], off
	global_load_dwordx4 v[214:217], v[104:105], off offset:128
	global_load_dwordx4 v[84:87], v[128:129], off
	global_load_dwordx4 v[88:91], v[130:131], off
	global_load_dwordx4 v[92:95], v[148:149], off
	global_load_dwordx4 v[96:99], v[104:105], off offset:64
	s_waitcnt vmcnt(4)
	v_sub_f32_e32 v83, v83, v100
	v_sub_f32_e32 v82, v82, v100
	v_sub_f32_e32 v81, v81, v100
	v_sub_f32_e32 v80, v80, v100
	v_pk_mul_f32 v[80:81], v[100:101], v[80:81] op_sel:[1,0]
	v_pk_mul_f32 v[82:83], v[100:101], v[82:83] op_sel:[1,0]
	s_waitcnt vmcnt(2)
	v_pk_fma_f32 v[80:81], v[80:81], v[84:85], v[88:89]
	v_pk_fma_f32 v[82:83], v[82:83], v[86:87], v[90:91]
	v_pk_mul_f32 v[80:81], v[80:81], s[2:3] op_sel_hi:[1,0]
	v_pk_mul_f32 v[82:83], v[82:83], s[2:3] op_sel_hi:[1,0]
	s_waitcnt vmcnt(1)
	v_pk_fma_f32 v[76:77], v[76:77], v[92:93], v[80:81]
	v_pk_fma_f32 v[78:79], v[78:79], v[94:95], v[82:83]
	global_store_dwordx4 v[104:105], v[76:79], off
	global_load_dwordx4 v[76:79], v[128:129], off offset:64
	s_nop 0
	global_load_dwordx4 v[80:83], v[130:131], off offset:64
	global_load_dwordx4 v[84:87], v[148:149], off offset:64
	v_mov_b32_e32 v88, v214
	v_mov_b32_e32 v89, v215
	v_mov_b32_e32 v90, v216
	v_mov_b32_e32 v91, v217
	s_waitcnt vmcnt(4)
	v_sub_f32_e32 v93, v99, v100
	v_sub_f32_e32 v92, v98, v100
	v_sub_f32_e32 v95, v97, v100
	v_sub_f32_e32 v94, v96, v100
	v_pk_mul_f32 v[94:95], v[100:101], v[94:95] op_sel:[1,0]
	v_pk_mul_f32 v[92:93], v[100:101], v[92:93] op_sel:[1,0]
	s_waitcnt vmcnt(1)
	v_pk_fma_f32 v[76:77], v[94:95], v[76:77], v[80:81]
	v_pk_fma_f32 v[78:79], v[92:93], v[78:79], v[82:83]
	v_pk_mul_f32 v[76:77], v[76:77], s[2:3] op_sel_hi:[1,0]
	v_pk_mul_f32 v[78:79], v[78:79], s[2:3] op_sel_hi:[1,0]
	s_waitcnt vmcnt(0)
; __device__ __forceinline__ void resid_tile256(const Params& p, int l, const bf16_t* A, int lda, int nk, const bf16_t* Wt, int ldb, int goff, bool x_from_input,
;                                               const float* lng, const float* lnb, int row0, int nt256, unsigned char* lds, int tid) {
;     ...
; #pragma unroll
;     for (int m = 0; m < 8; ++m) {
;         const int lr = wr * 128 + m * 16 + fr, pp = pp0 + lr;
;         const float* xi = x_rd(p, x_from_input, b, pp);
;         float* xo = x_wr(p, b, pp);
;         float mean = 0.f, rstd = 1.f;
;         if (!x_from_input) { const size_t row = (size_t)row0 + lr; mean = stats[row * 2]; rstd = stats[row * 2 + 1]; }
; #pragma unroll
;         for (int n = 0; n < 4; ++n) {
;             const int col = nt256 * 256 + wc * 64 + n * 16 + fq * 4;
;             f32x4 xv = *(const f32x4*)(xi + col); const f32x4 g4 = *(const f32x4*)(gv + col);
;             if (!x_from_input) {
;                 const f32x4 lg = *(const f32x4*)(lng + col), lb = *(const f32x4*)(lnb + col);
; #pragma unroll
;                 for (int j = 0; j < 4; ++j) xv[j] = (xv[j] - mean) * rstd * lg[j] + lb[j];
;             }
;             f32x4 o;
; #pragma unroll
;             for (int j = 0; j < 4; ++j) o[j] = ALPHA * xv[j] + g4[j] * acc[m][n][j];
;             *(f32x4*)(xo + col) = o;
;         }
	v_pk_fma_f32 v[72:73], v[72:73], v[84:85], v[76:77]
	v_pk_fma_f32 v[74:75], v[74:75], v[86:87], v[78:79]
	global_store_dwordx4 v[104:105], v[72:75], off offset:64
	global_load_dwordx4 v[72:75], v[128:129], off offset:128
	s_nop 0
	global_load_dwordx4 v[76:79], v[130:131], off offset:128
	global_load_dwordx4 v[80:83], v[148:149], off offset:128
	global_load_dwordx4 v[84:87], v[104:105], off offset:192
	s_waitcnt vmcnt(5)
	v_sub_f32_e32 v91, v91, v100
	v_sub_f32_e32 v90, v90, v100
	v_sub_f32_e32 v89, v89, v100
	v_sub_f32_e32 v88, v88, v100
	v_pk_mul_f32 v[88:89], v[100:101], v[88:89] op_sel:[1,0]
	v_pk_mul_f32 v[90:91], v[100:101], v[90:91] op_sel:[1,0]
	s_waitcnt vmcnt(2)
	v_pk_fma_f32 v[72:73], v[88:89], v[72:73], v[76:77]
	v_pk_fma_f32 v[74:75], v[90:91], v[74:75], v[78:79]
	v_pk_mul_f32 v[72:73], v[72:73], s[2:3] op_sel_hi:[1,0]
	v_pk_mul_f32 v[74:75], v[74:75], s[2:3] op_sel_hi:[1,0]
	s_waitcnt vmcnt(1)
	v_pk_fma_f32 v[68:69], v[68:69], v[80:81], v[72:73]
	v_pk_fma_f32 v[70:71], v[70:71], v[82:83], v[74:75]
	global_store_dwordx4 v[104:105], v[68:71], off offset:128
	global_load_dwordx4 v[68:71], v[128:129], off offset:192
	s_nop 0
	global_load_dwordx4 v[72:75], v[130:131], off offset:192
	global_load_dwordx4 v[76:79], v[148:149], off offset:192
	v_add_u32_e32 v82, s71, v140
	v_add_u32_e32 v88, 0xffffff00, v82
	v_ashrrev_i32_e32 v83, 31, v82
	v_cmp_gt_i32_e32 vcc, s88, v82
	s_waitcnt vmcnt(4)
	v_sub_f32_e32 v85, v85, v100
	v_sub_f32_e32 v84, v84, v100
	v_cndmask_b32_e32 v83, 0, v83, vcc
	v_cndmask_b32_e32 v82, v88, v82, vcc
	v_lshlrev_b64 v[82:83], 12, v[82:83]
	v_cndmask_b32_e32 v88, v154, v155, vcc
	v_cndmask_b32_e32 v89, v152, v153, vcc
	v_lshl_add_u64 v[82:83], v[88:89], 0, v[82:83]
	v_lshl_add_u64 v[88:89], v[82:83], 0, v[150:151]
	v_sub_f32_e32 v83, v87, v100
	v_sub_f32_e32 v82, v86, v100
	v_pk_mul_f32 v[84:85], v[100:101], v[84:85] op_sel:[1,0]
	v_pk_mul_f32 v[82:83], v[100:101], v[82:83] op_sel:[1,0]
	v_lshl_add_u64 v[80:81], s[48:49], 0, v[140:141]
	v_lshl_add_u64 v[80:81], v[80:81], 3, s[46:47]
	s_waitcnt vmcnt(1)
	v_pk_fma_f32 v[70:71], v[82:83], v[70:71], v[74:75]
	v_pk_fma_f32 v[68:69], v[84:85], v[68:69], v[72:73]
	v_pk_mul_f32 v[70:71], v[70:71], s[2:3] op_sel_hi:[1,0]
	v_pk_mul_f32 v[68:69], v[68:69], s[2:3] op_sel_hi:[1,0]
	s_waitcnt vmcnt(0)
	v_pk_fma_f32 v[66:67], v[66:67], v[78:79], v[70:71]
	v_pk_fma_f32 v[64:65], v[64:65], v[76:77], v[68:69]
	global_store_dwordx4 v[104:105], v[64:67], off offset:192
	global_load_dwordx2 v[84:85], v[80:81], off
	s_nop 0
	global_load_dwordx4 v[64:67], v[88:89], off
	global_load_dwordx4 v[214:217], v[88:89], off offset:128
	global_load_dwordx4 v[68:71], v[128:129], off
	global_load_dwordx4 v[72:75], v[130:131], off
	global_load_dwordx4 v[76:79], v[148:149], off
	global_load_dwordx4 v[80:83], v[88:89], off offset:64
	s_waitcnt vmcnt(4)
	v_sub_f32_e32 v67, v67, v84
	v_sub_f32_e32 v66, v66, v84
	v_sub_f32_e32 v65, v65, v84
	v_sub_f32_e32 v64, v64, v84
	v_pk_mul_f32 v[64:65], v[84:85], v[64:65] op_sel:[1,0]
	v_pk_mul_f32 v[66:67], v[84:85], v[66:67] op_sel:[1,0]
	s_waitcnt vmcnt(2)
	v_pk_fma_f32 v[64:65], v[64:65], v[68:69], v[72:73]
	v_pk_fma_f32 v[66:67], v[66:67], v[70:71], v[74:75]
	v_pk_mul_f32 v[64:65], v[64:65], s[2:3] op_sel_hi:[1,0]
	v_pk_mul_f32 v[66:67], v[66:67], s[2:3] op_sel_hi:[1,0]
	s_waitcnt vmcnt(1)
	v_pk_fma_f32 v[60:61], v[60:61], v[76:77], v[64:65]
	v_pk_fma_f32 v[62:63], v[62:63], v[78:79], v[66:67]
	global_store_dwordx4 v[88:89], v[60:63], off
	global_load_dwordx4 v[60:63], v[128:129], off offset:64
	s_nop 0
	global_load_dwordx4 v[64:67], v[130:131], off offset:64
	global_load_dwordx4 v[68:71], v[148:149], off offset:64
	v_mov_b32_e32 v72, v214
	v_mov_b32_e32 v73, v215
	v_mov_b32_e32 v74, v216
	v_mov_b32_e32 v75, v217
	s_waitcnt vmcnt(4)
	v_sub_f32_e32 v77, v83, v84
	v_sub_f32_e32 v76, v82, v84
	v_sub_f32_e32 v79, v81, v84
	v_sub_f32_e32 v78, v80, v84
	v_pk_mul_f32 v[78:79], v[84:85], v[78:79] op_sel:[1,0]
	v_pk_mul_f32 v[76:77], v[84:85], v[76:77] op_sel:[1,0]
	s_waitcnt vmcnt(1)
	v_pk_fma_f32 v[60:61], v[78:79], v[60:61], v[64:65]
	v_pk_fma_f32 v[62:63], v[76:77], v[62:63], v[66:67]
	v_pk_mul_f32 v[60:61], v[60:61], s[2:3] op_sel_hi:[1,0]
	v_pk_mul_f32 v[62:63], v[62:63], s[2:3] op_sel_hi:[1,0]
	s_waitcnt vmcnt(0)
	v_pk_fma_f32 v[56:57], v[56:57], v[68:69], v[60:61]
	v_pk_fma_f32 v[58:59], v[58:59], v[70:71], v[62:63]
	global_store_dwordx4 v[88:89], v[56:59], off offset:64
	global_load_dwordx4 v[56:59], v[128:129], off offset:128
	s_nop 0
	global_load_dwordx4 v[60:63], v[130:131], off offset:128
	global_load_dwordx4 v[64:67], v[148:149], off offset:128
	global_load_dwordx4 v[68:71], v[88:89], off offset:192
	s_waitcnt vmcnt(5)
	v_sub_f32_e32 v75, v75, v84
	v_sub_f32_e32 v74, v74, v84
	v_sub_f32_e32 v73, v73, v84
	v_sub_f32_e32 v72, v72, v84
	v_pk_mul_f32 v[72:73], v[84:85], v[72:73] op_sel:[1,0]
	v_pk_mul_f32 v[74:75], v[84:85], v[74:75] op_sel:[1,0]
	s_waitcnt vmcnt(2)
	v_pk_fma_f32 v[56:57], v[72:73], v[56:57], v[60:61]
	v_pk_fma_f32 v[58:59], v[74:75], v[58:59], v[62:63]
	v_pk_mul_f32 v[56:57], v[56:57], s[2:3] op_sel_hi:[1,0]
	v_pk_mul_f32 v[58:59], v[58:59], s[2:3] op_sel_hi:[1,0]
	s_waitcnt vmcnt(1)
	v_pk_fma_f32 v[52:53], v[52:53], v[64:65], v[56:57]
	v_pk_fma_f32 v[54:55], v[54:55], v[66:67], v[58:59]
	global_store_dwordx4 v[88:89], v[52:55], off offset:128
	global_load_dwordx4 v[52:55], v[128:129], off offset:192
	s_nop 0
	global_load_dwordx4 v[56:59], v[130:131], off offset:192
	global_load_dwordx4 v[60:63], v[148:149], off offset:192
	v_add_u32_e32 v66, s71, v142
	v_add_u32_e32 v72, 0xffffff00, v66
	v_ashrrev_i32_e32 v67, 31, v66
	v_cmp_gt_i32_e32 vcc, s88, v66
	s_waitcnt vmcnt(4)
; __device__ __forceinline__ void resid_tile256(const Params& p, int l, const bf16_t* A, int lda, int nk, const bf16_t* Wt, int ldb, int goff, bool x_from_input,
;                                               const float* lng, const float* lnb, int row0, int nt256, unsigned char* lds, int tid) {
;     ...
; #pragma unroll
;     for (int m = 0; m < 8; ++m) {
;         const int lr = wr * 128 + m * 16 + fr, pp = pp0 + lr;
;         const float* xi = x_rd(p, x_from_input, b, pp);
;         float* xo = x_wr(p, b, pp);
;         float mean = 0.f, rstd = 1.f;
;         if (!x_from_input) { const size_t row = (size_t)row0 + lr; mean = stats[row * 2]; rstd = stats[row * 2 + 1]; }
; #pragma unroll
;         for (int n = 0; n < 4; ++n) {
;             const int col = nt256 * 256 + wc * 64 + n * 16 + fq * 4;
;             f32x4 xv = *(const f32x4*)(xi + col); const f32x4 g4 = *(const f32x4*)(gv + col);
;             if (!x_from_input) {
;                 const f32x4 lg = *(const f32x4*)(lng + col), lb = *(const f32x4*)(lnb + col);
; #pragma unroll
;                 for (int j = 0; j < 4; ++j) xv[j] = (xv[j] - mean) * rstd * lg[j] + lb[j];
;             }
;             f32x4 o;
; #pragma unroll
;             for (int j = 0; j < 4; ++j) o[j] = ALPHA * xv[j] + g4[j] * acc[m][n][j];
;             *(f32x4*)(xo + col) = o;
;         }
	v_sub_f32_e32 v69, v69, v84
	v_sub_f32_e32 v68, v68, v84
	v_cndmask_b32_e32 v67, 0, v67, vcc
	v_cndmask_b32_e32 v66, v72, v66, vcc
	v_lshlrev_b64 v[66:67], 12, v[66:67]
	v_cndmask_b32_e32 v72, v154, v155, vcc
	v_cndmask_b32_e32 v73, v152, v153, vcc
	v_lshl_add_u64 v[66:67], v[72:73], 0, v[66:67]
	v_lshl_add_u64 v[72:73], v[66:67], 0, v[150:151]
	v_sub_f32_e32 v67, v71, v84
	v_sub_f32_e32 v66, v70, v84
	v_pk_mul_f32 v[68:69], v[84:85], v[68:69] op_sel:[1,0]
	v_pk_mul_f32 v[66:67], v[84:85], v[66:67] op_sel:[1,0]
	v_lshl_add_u64 v[64:65], s[48:49], 0, v[142:143]
	v_lshl_add_u64 v[64:65], v[64:65], 3, s[46:47]
	s_waitcnt vmcnt(1)
	v_pk_fma_f32 v[54:55], v[66:67], v[54:55], v[58:59]
	v_pk_fma_f32 v[52:53], v[68:69], v[52:53], v[56:57]
	v_pk_mul_f32 v[54:55], v[54:55], s[2:3] op_sel_hi:[1,0]
	v_pk_mul_f32 v[52:53], v[52:53], s[2:3] op_sel_hi:[1,0]
	s_waitcnt vmcnt(0)
	v_pk_fma_f32 v[50:51], v[50:51], v[62:63], v[54:55]
	v_pk_fma_f32 v[48:49], v[48:49], v[60:61], v[52:53]
	global_store_dwordx4 v[88:89], v[48:51], off offset:192
	global_load_dwordx2 v[68:69], v[64:65], off
	s_nop 0
	global_load_dwordx4 v[48:51], v[72:73], off
	global_load_dwordx4 v[214:217], v[72:73], off offset:128
	global_load_dwordx4 v[52:55], v[128:129], off
	global_load_dwordx4 v[56:59], v[130:131], off
	global_load_dwordx4 v[60:63], v[148:149], off
	global_load_dwordx4 v[64:67], v[72:73], off offset:64
	s_waitcnt vmcnt(4)
	v_sub_f32_e32 v51, v51, v68
	v_sub_f32_e32 v50, v50, v68
	v_sub_f32_e32 v49, v49, v68
	v_sub_f32_e32 v48, v48, v68
	v_pk_mul_f32 v[48:49], v[68:69], v[48:49] op_sel:[1,0]
	v_pk_mul_f32 v[50:51], v[68:69], v[50:51] op_sel:[1,0]
	s_waitcnt vmcnt(2)
	v_pk_fma_f32 v[48:49], v[48:49], v[52:53], v[56:57]
	v_pk_fma_f32 v[50:51], v[50:51], v[54:55], v[58:59]
	v_pk_mul_f32 v[48:49], v[48:49], s[2:3] op_sel_hi:[1,0]
	v_pk_mul_f32 v[50:51], v[50:51], s[2:3] op_sel_hi:[1,0]
	s_waitcnt vmcnt(1)
	v_pk_fma_f32 v[44:45], v[44:45], v[60:61], v[48:49]
	v_pk_fma_f32 v[46:47], v[46:47], v[62:63], v[50:51]
	global_store_dwordx4 v[72:73], v[44:47], off
	global_load_dwordx4 v[44:47], v[128:129], off offset:64
	s_nop 0
	global_load_dwordx4 v[48:51], v[130:131], off offset:64
	global_load_dwordx4 v[52:55], v[148:149], off offset:64
	v_mov_b32_e32 v56, v214
	v_mov_b32_e32 v57, v215
	v_mov_b32_e32 v58, v216
	v_mov_b32_e32 v59, v217
	s_waitcnt vmcnt(4)
	v_sub_f32_e32 v61, v67, v68
	v_sub_f32_e32 v60, v66, v68
	v_sub_f32_e32 v63, v65, v68
	v_sub_f32_e32 v62, v64, v68
	v_pk_mul_f32 v[62:63], v[68:69], v[62:63] op_sel:[1,0]
	v_pk_mul_f32 v[60:61], v[68:69], v[60:61] op_sel:[1,0]
	s_waitcnt vmcnt(1)
	v_pk_fma_f32 v[44:45], v[62:63], v[44:45], v[48:49]
	v_pk_fma_f32 v[46:47], v[60:61], v[46:47], v[50:51]
	v_pk_mul_f32 v[44:45], v[44:45], s[2:3] op_sel_hi:[1,0]
	v_pk_mul_f32 v[46:47], v[46:47], s[2:3] op_sel_hi:[1,0]
	s_waitcnt vmcnt(0)
	v_pk_fma_f32 v[40:41], v[40:41], v[52:53], v[44:45]
	v_pk_fma_f32 v[42:43], v[42:43], v[54:55], v[46:47]
	global_store_dwordx4 v[72:73], v[40:43], off offset:64
	global_load_dwordx4 v[40:43], v[128:129], off offset:128
	s_nop 0
	global_load_dwordx4 v[44:47], v[130:131], off offset:128
	global_load_dwordx4 v[48:51], v[148:149], off offset:128
	global_load_dwordx4 v[52:55], v[72:73], off offset:192
	s_waitcnt vmcnt(5)
	v_sub_f32_e32 v59, v59, v68
	v_sub_f32_e32 v58, v58, v68
	v_sub_f32_e32 v57, v57, v68
	v_sub_f32_e32 v56, v56, v68
	v_pk_mul_f32 v[56:57], v[68:69], v[56:57] op_sel:[1,0]
	v_pk_mul_f32 v[58:59], v[68:69], v[58:59] op_sel:[1,0]
	s_waitcnt vmcnt(2)
	v_pk_fma_f32 v[40:41], v[56:57], v[40:41], v[44:45]
	v_pk_fma_f32 v[42:43], v[58:59], v[42:43], v[46:47]
	v_pk_mul_f32 v[40:41], v[40:41], s[2:3] op_sel_hi:[1,0]
	v_pk_mul_f32 v[42:43], v[42:43], s[2:3] op_sel_hi:[1,0]
	s_waitcnt vmcnt(1)
	v_pk_fma_f32 v[36:37], v[36:37], v[48:49], v[40:41]
	v_pk_fma_f32 v[38:39], v[38:39], v[50:51], v[42:43]
	global_store_dwordx4 v[72:73], v[36:39], off offset:128
	global_load_dwordx4 v[36:39], v[128:129], off offset:192
	s_nop 0
	global_load_dwordx4 v[40:43], v[130:131], off offset:192
	global_load_dwordx4 v[44:47], v[148:149], off offset:192
	v_add_u32_e32 v50, s71, v144
	v_add_u32_e32 v56, 0xffffff00, v50
	v_ashrrev_i32_e32 v51, 31, v50
	v_cmp_gt_i32_e32 vcc, s88, v50
	s_waitcnt vmcnt(4)
	v_sub_f32_e32 v53, v53, v68
	v_sub_f32_e32 v52, v52, v68
	v_cndmask_b32_e32 v51, 0, v51, vcc
	v_cndmask_b32_e32 v50, v56, v50, vcc
	v_lshlrev_b64 v[50:51], 12, v[50:51]
	v_cndmask_b32_e32 v56, v154, v155, vcc
	v_cndmask_b32_e32 v57, v152, v153, vcc
	v_lshl_add_u64 v[50:51], v[56:57], 0, v[50:51]
	v_lshl_add_u64 v[56:57], v[50:51], 0, v[150:151]
	v_sub_f32_e32 v51, v55, v68
	v_sub_f32_e32 v50, v54, v68
	v_pk_mul_f32 v[52:53], v[68:69], v[52:53] op_sel:[1,0]
	v_pk_mul_f32 v[50:51], v[68:69], v[50:51] op_sel:[1,0]
	v_lshl_add_u64 v[48:49], s[48:49], 0, v[144:145]
	v_lshl_add_u64 v[48:49], v[48:49], 3, s[46:47]
	s_waitcnt vmcnt(1)
	v_pk_fma_f32 v[38:39], v[50:51], v[38:39], v[42:43]
	v_pk_fma_f32 v[36:37], v[52:53], v[36:37], v[40:41]
	v_pk_mul_f32 v[38:39], v[38:39], s[2:3] op_sel_hi:[1,0]
	v_pk_mul_f32 v[36:37], v[36:37], s[2:3] op_sel_hi:[1,0]
	s_waitcnt vmcnt(0)
	v_pk_fma_f32 v[34:35], v[34:35], v[46:47], v[38:39]
	v_pk_fma_f32 v[32:33], v[32:33], v[44:45], v[36:37]
	global_store_dwordx4 v[72:73], v[32:35], off offset:192
	global_load_dwordx2 v[52:53], v[48:49], off
	s_nop 0
	global_load_dwordx4 v[32:35], v[56:57], off
	global_load_dwordx4 v[214:217], v[56:57], off offset:128
	global_load_dwordx4 v[36:39], v[128:129], off
	global_load_dwordx4 v[40:43], v[130:131], off
	global_load_dwordx4 v[44:47], v[148:149], off
	global_load_dwordx4 v[48:51], v[56:57], off offset:64
	s_waitcnt vmcnt(4)
; __device__ __forceinline__ void resid_tile256(const Params& p, int l, const bf16_t* A, int lda, int nk, const bf16_t* Wt, int ldb, int goff, bool x_from_input,
;                                               const float* lng, const float* lnb, int row0, int nt256, unsigned char* lds, int tid) {
;     ...
; #pragma unroll
;     for (int m = 0; m < 8; ++m) {
;         const int lr = wr * 128 + m * 16 + fr, pp = pp0 + lr;
;         const float* xi = x_rd(p, x_from_input, b, pp);
;         float* xo = x_wr(p, b, pp);
;         float mean = 0.f, rstd = 1.f;
;         if (!x_from_input) { const size_t row = (size_t)row0 + lr; mean = stats[row * 2]; rstd = stats[row * 2 + 1]; }
; #pragma unroll
;         for (int n = 0; n < 4; ++n) {
;             const int col = nt256 * 256 + wc * 64 + n * 16 + fq * 4;
;             f32x4 xv = *(const f32x4*)(xi + col); const f32x4 g4 = *(const f32x4*)(gv + col);
;             if (!x_from_input) {
;                 const f32x4 lg = *(const f32x4*)(lng + col), lb = *(const f32x4*)(lnb + col);
; #pragma unroll
;                 for (int j = 0; j < 4; ++j) xv[j] = (xv[j] - mean) * rstd * lg[j] + lb[j];
;             }
;             f32x4 o;
; #pragma unroll
;             for (int j = 0; j < 4; ++j) o[j] = ALPHA * xv[j] + g4[j] * acc[m][n][j];
;             *(f32x4*)(xo + col) = o;
;         }
	v_sub_f32_e32 v35, v35, v52
	v_sub_f32_e32 v34, v34, v52
	v_sub_f32_e32 v33, v33, v52
	v_sub_f32_e32 v32, v32, v52
	v_pk_mul_f32 v[32:33], v[52:53], v[32:33] op_sel:[1,0]
	v_pk_mul_f32 v[34:35], v[52:53], v[34:35] op_sel:[1,0]
	s_waitcnt vmcnt(2)
	v_pk_fma_f32 v[32:33], v[32:33], v[36:37], v[40:41]
	v_pk_fma_f32 v[34:35], v[34:35], v[38:39], v[42:43]
	v_pk_mul_f32 v[32:33], v[32:33], s[2:3] op_sel_hi:[1,0]
	v_pk_mul_f32 v[34:35], v[34:35], s[2:3] op_sel_hi:[1,0]
	s_waitcnt vmcnt(1)
	v_pk_fma_f32 v[28:29], v[28:29], v[44:45], v[32:33]
	v_pk_fma_f32 v[30:31], v[30:31], v[46:47], v[34:35]
	global_store_dwordx4 v[56:57], v[28:31], off
	global_load_dwordx4 v[28:31], v[128:129], off offset:64
	s_nop 0
	global_load_dwordx4 v[32:35], v[130:131], off offset:64
	global_load_dwordx4 v[36:39], v[148:149], off offset:64
	v_mov_b32_e32 v40, v214
	v_mov_b32_e32 v41, v215
	v_mov_b32_e32 v42, v216
	v_mov_b32_e32 v43, v217
	s_waitcnt vmcnt(4)
	v_sub_f32_e32 v45, v51, v52
	v_sub_f32_e32 v44, v50, v52
	v_sub_f32_e32 v47, v49, v52
	v_sub_f32_e32 v46, v48, v52
	v_pk_mul_f32 v[46:47], v[52:53], v[46:47] op_sel:[1,0]
	v_pk_mul_f32 v[44:45], v[52:53], v[44:45] op_sel:[1,0]
	s_waitcnt vmcnt(1)
	v_pk_fma_f32 v[28:29], v[46:47], v[28:29], v[32:33]
	v_pk_fma_f32 v[30:31], v[44:45], v[30:31], v[34:35]
	v_pk_mul_f32 v[28:29], v[28:29], s[2:3] op_sel_hi:[1,0]
	v_pk_mul_f32 v[30:31], v[30:31], s[2:3] op_sel_hi:[1,0]
	s_waitcnt vmcnt(0)
	v_pk_fma_f32 v[24:25], v[24:25], v[36:37], v[28:29]
	v_pk_fma_f32 v[26:27], v[26:27], v[38:39], v[30:31]
	global_store_dwordx4 v[56:57], v[24:27], off offset:64
	global_load_dwordx4 v[24:27], v[128:129], off offset:128
	s_nop 0
	global_load_dwordx4 v[28:31], v[130:131], off offset:128
	global_load_dwordx4 v[32:35], v[148:149], off offset:128
	global_load_dwordx4 v[36:39], v[56:57], off offset:192
	s_waitcnt vmcnt(5)
	v_sub_f32_e32 v43, v43, v52
	v_sub_f32_e32 v42, v42, v52
	v_sub_f32_e32 v41, v41, v52
	v_sub_f32_e32 v40, v40, v52
	v_pk_mul_f32 v[40:41], v[52:53], v[40:41] op_sel:[1,0]
	v_pk_mul_f32 v[42:43], v[52:53], v[42:43] op_sel:[1,0]
	s_waitcnt vmcnt(2)
	v_pk_fma_f32 v[24:25], v[40:41], v[24:25], v[28:29]
	v_pk_fma_f32 v[26:27], v[42:43], v[26:27], v[30:31]
	v_pk_mul_f32 v[24:25], v[24:25], s[2:3] op_sel_hi:[1,0]
	v_pk_mul_f32 v[26:27], v[26:27], s[2:3] op_sel_hi:[1,0]
	s_waitcnt vmcnt(1)
	v_pk_fma_f32 v[20:21], v[20:21], v[32:33], v[24:25]
	v_pk_fma_f32 v[22:23], v[22:23], v[34:35], v[26:27]
	global_store_dwordx4 v[56:57], v[20:23], off offset:128
	global_load_dwordx4 v[20:23], v[128:129], off offset:192
	s_nop 0
	global_load_dwordx4 v[24:27], v[130:131], off offset:192
	global_load_dwordx4 v[28:31], v[148:149], off offset:192
	v_add_u32_e32 v34, s71, v146
	v_add_u32_e32 v40, 0xffffff00, v34
	v_ashrrev_i32_e32 v35, 31, v34
	v_cmp_gt_i32_e32 vcc, s88, v34
	s_waitcnt vmcnt(4)
	v_sub_f32_e32 v37, v37, v52
	v_sub_f32_e32 v36, v36, v52
	v_cndmask_b32_e32 v35, 0, v35, vcc
	v_cndmask_b32_e32 v34, v40, v34, vcc
	v_lshlrev_b64 v[34:35], 12, v[34:35]
	v_cndmask_b32_e32 v40, v154, v155, vcc
	v_cndmask_b32_e32 v41, v152, v153, vcc
	v_lshl_add_u64 v[34:35], v[40:41], 0, v[34:35]
	v_lshl_add_u64 v[40:41], v[34:35], 0, v[150:151]
	v_sub_f32_e32 v35, v39, v52
	v_sub_f32_e32 v34, v38, v52
	v_pk_mul_f32 v[36:37], v[52:53], v[36:37] op_sel:[1,0]
	v_pk_mul_f32 v[34:35], v[52:53], v[34:35] op_sel:[1,0]
	v_lshl_add_u64 v[32:33], s[48:49], 0, v[146:147]
	v_lshl_add_u64 v[32:33], v[32:33], 3, s[46:47]
	s_waitcnt vmcnt(1)
	v_pk_fma_f32 v[22:23], v[34:35], v[22:23], v[26:27]
	v_pk_fma_f32 v[20:21], v[36:37], v[20:21], v[24:25]
	v_pk_mul_f32 v[22:23], v[22:23], s[2:3] op_sel_hi:[1,0]
	v_pk_mul_f32 v[20:21], v[20:21], s[2:3] op_sel_hi:[1,0]
	s_waitcnt vmcnt(0)
; __device__ __forceinline__ void resid_tile256(const Params& p, int l, const bf16_t* A, int lda, int nk, const bf16_t* Wt, int ldb, int goff, bool x_from_input,
;                                               const float* lng, const float* lnb, int row0, int nt256, unsigned char* lds, int tid) {
;     ...
;     for (int m = 0; m < 8; ++m) {
;         const int lr = wr * 128 + m * 16 + fr, pp = pp0 + lr;
;         const float* xi = x_rd(p, x_from_input, b, pp);
;         float* xo = x_wr(p, b, pp);
;         float mean = 0.f, rstd = 1.f;
;         if (!x_from_input) { const size_t row = (size_t)row0 + lr; mean = stats[row * 2]; rstd = stats[row * 2 + 1]; }
; #pragma unroll
;         for (int n = 0; n < 4; ++n) {
;             const int col = nt256 * 256 + wc * 64 + n * 16 + fq * 4;
;             f32x4 xv = *(const f32x4*)(xi + col); const f32x4 g4 = *(const f32x4*)(gv + col);
;             if (!x_from_input) {
;                 const f32x4 lg = *(const f32x4*)(lng + col), lb = *(const f32x4*)(lnb + col);
; #pragma unroll
;                 for (int j = 0; j < 4; ++j) xv[j] = (xv[j] - mean) * rstd * lg[j] + lb[j];
;             }
;             f32x4 o;
; #pragma unroll
;             for (int j = 0; j < 4; ++j) o[j] = ALPHA * xv[j] + g4[j] * acc[m][n][j];
;             *(f32x4*)(xo + col) = o;
;         }
	v_pk_fma_f32 v[18:19], v[18:19], v[30:31], v[22:23]
	v_pk_fma_f32 v[16:17], v[16:17], v[28:29], v[20:21]
	global_store_dwordx4 v[56:57], v[16:19], off offset:192
	global_load_dwordx2 v[36:37], v[32:33], off
	s_nop 0
	global_load_dwordx4 v[16:19], v[40:41], off
	global_load_dwordx4 v[214:217], v[40:41], off offset:128
	global_load_dwordx4 v[20:23], v[128:129], off
	global_load_dwordx4 v[24:27], v[130:131], off
	global_load_dwordx4 v[28:31], v[148:149], off
	global_load_dwordx4 v[32:35], v[40:41], off offset:64
	s_waitcnt vmcnt(4)
	v_sub_f32_e32 v19, v19, v36
	v_sub_f32_e32 v18, v18, v36
	v_sub_f32_e32 v17, v17, v36
	v_sub_f32_e32 v16, v16, v36
	v_pk_mul_f32 v[16:17], v[36:37], v[16:17] op_sel:[1,0]
	v_pk_mul_f32 v[18:19], v[36:37], v[18:19] op_sel:[1,0]
	s_waitcnt vmcnt(2)
	v_pk_fma_f32 v[16:17], v[16:17], v[20:21], v[24:25]
	v_pk_fma_f32 v[18:19], v[18:19], v[22:23], v[26:27]
	v_pk_mul_f32 v[16:17], v[16:17], s[2:3] op_sel_hi:[1,0]
	v_pk_mul_f32 v[18:19], v[18:19], s[2:3] op_sel_hi:[1,0]
	s_waitcnt vmcnt(1)
	v_pk_fma_f32 v[12:13], v[12:13], v[28:29], v[16:17]
	v_pk_fma_f32 v[14:15], v[14:15], v[30:31], v[18:19]
	global_store_dwordx4 v[40:41], v[12:15], off
	global_load_dwordx4 v[12:15], v[128:129], off offset:64
	s_nop 0
	global_load_dwordx4 v[16:19], v[130:131], off offset:64
	global_load_dwordx4 v[20:23], v[148:149], off offset:64
	v_mov_b32_e32 v24, v214
	v_mov_b32_e32 v25, v215
	v_mov_b32_e32 v26, v216
	v_mov_b32_e32 v27, v217
	s_waitcnt vmcnt(4)
	v_sub_f32_e32 v29, v35, v36
	v_sub_f32_e32 v28, v34, v36
	v_sub_f32_e32 v31, v33, v36
	v_sub_f32_e32 v30, v32, v36
	v_pk_mul_f32 v[30:31], v[36:37], v[30:31] op_sel:[1,0]
	v_pk_mul_f32 v[28:29], v[36:37], v[28:29] op_sel:[1,0]
	s_waitcnt vmcnt(1)
	v_pk_fma_f32 v[12:13], v[30:31], v[12:13], v[16:17]
	v_pk_fma_f32 v[14:15], v[28:29], v[14:15], v[18:19]
	v_pk_mul_f32 v[12:13], v[12:13], s[2:3] op_sel_hi:[1,0]
	v_pk_mul_f32 v[14:15], v[14:15], s[2:3] op_sel_hi:[1,0]
	s_waitcnt vmcnt(0)
	v_pk_fma_f32 v[4:5], v[4:5], v[20:21], v[12:13]
	v_pk_fma_f32 v[6:7], v[6:7], v[22:23], v[14:15]
	global_store_dwordx4 v[40:41], v[4:7], off offset:64
	global_load_dwordx4 v[4:7], v[128:129], off offset:128
	s_nop 0
	global_load_dwordx4 v[12:15], v[130:131], off offset:128
	global_load_dwordx4 v[16:19], v[148:149], off offset:128
	global_load_dwordx4 v[20:23], v[40:41], off offset:192
	s_waitcnt vmcnt(5)
	v_sub_f32_e32 v27, v27, v36
	v_sub_f32_e32 v26, v26, v36
	v_sub_f32_e32 v25, v25, v36
	v_sub_f32_e32 v24, v24, v36
	v_pk_mul_f32 v[24:25], v[36:37], v[24:25] op_sel:[1,0]
	v_pk_mul_f32 v[26:27], v[36:37], v[26:27] op_sel:[1,0]
	s_waitcnt vmcnt(2)
	v_pk_fma_f32 v[4:5], v[24:25], v[4:5], v[12:13]
	v_pk_fma_f32 v[6:7], v[26:27], v[6:7], v[14:15]
	v_pk_mul_f32 v[4:5], v[4:5], s[2:3] op_sel_hi:[1,0]
	v_pk_mul_f32 v[6:7], v[6:7], s[2:3] op_sel_hi:[1,0]
	s_waitcnt vmcnt(1)
	v_pk_fma_f32 v[0:1], v[0:1], v[16:17], v[4:5]
	v_pk_fma_f32 v[2:3], v[2:3], v[18:19], v[6:7]
	global_store_dwordx4 v[40:41], v[0:3], off offset:128
	global_load_dwordx4 v[0:3], v[128:129], off offset:192
	s_nop 0
	global_load_dwordx4 v[4:7], v[130:131], off offset:192
	global_load_dwordx4 v[12:15], v[148:149], off offset:192
	s_waitcnt vmcnt(4)
	v_sub_f32_e32 v17, v23, v36
	v_sub_f32_e32 v16, v22, v36
	v_sub_f32_e32 v19, v21, v36
	v_sub_f32_e32 v18, v20, v36
	v_pk_mul_f32 v[18:19], v[36:37], v[18:19] op_sel:[1,0]
	v_pk_mul_f32 v[16:17], v[36:37], v[16:17] op_sel:[1,0]
	s_waitcnt vmcnt(1)
	v_pk_fma_f32 v[0:1], v[18:19], v[0:1], v[4:5]
	v_pk_fma_f32 v[2:3], v[16:17], v[2:3], v[6:7]
	v_pk_mul_f32 v[0:1], v[0:1], s[2:3] op_sel_hi:[1,0]
	v_pk_mul_f32 v[2:3], v[2:3], s[2:3] op_sel_hi:[1,0]
	s_waitcnt vmcnt(0)
	v_pk_fma_f32 v[0:1], v[8:9], v[12:13], v[0:1]
	v_pk_fma_f32 v[2:3], v[10:11], v[14:15], v[2:3]
	global_store_dwordx4 v[40:41], v[0:3], off offset:192
